# hand-written sequential recurrence loops (HG+GLA): one barrier per chunk step, deferred rmsnorm/store, f32 OT staging
# speedup vs baseline: 1.0200x; 1.0200x over previous
; template <int DK, bool HG, int MODE>
; __device__ void recur_unit(const Params& p, char* smem, int b, int h, char* img, int nstart, int nstep, int nend) {
;     ...
;   const int tid = threadIdx.x, lane = tid & 63, w = tid >> 6, l15 = lane & 15, kg = lane >> 4;
;   const int t = tid & 15, kgp = tid >> 4, k0 = kgp * KPT;
;   const int qcol = HG ? (h * 128) : (2048 + h * 64);
;   const int kcol = HG ? (512 + h * 128) : (2304 + h * 64);
;   const int vcol = HG ? (1024 + h * 128) : (2560 + h * 128);
;   const int gcol = HG ? (1536 + h * 128) : (3088 + h * 128);
;   const int ocol = HG ? (h * 128) : (512 + h * 128);
;   const float* gain = HG ? p.norm_h : p.norm_g;
;   float ba[KPT];
;   if (!HG && MODE == 1) {
;     __syncthreads();
;     for (int i = tid; i < 16 * 64; i += 256) Wa[i] = p.w_a2[(i >> 6) * 256 + h * 64 + (i & 63)];
; #pragma unroll
;     for (int i = 0; i < KPT; i++) ba[i] = p.b_a[h * 64 + k0 + i];
;     __syncthreads();
;   }
;   const float g0 = gain[h * 128 + w * 32 + l15], g1 = gain[h * 128 + w * 32 + 16 + l15];
;   f32x4 S[NKT][2];
; #pragma unroll
;   for (int i = 0; i < NKT; i++) { S[i][0] = f32x4{0, 0, 0, 0}; S[i][1] = f32x4{0, 0, 0, 0}; }
;   float4 pl[4];
;   uint4 pq, pk, pv;
;   u16 psg[8];
;   u32x4 imA[NIM], imB[NIM];
;   u16 psgB[8];
;   auto prefetch = [&](int n, u32x4 (&im)[NIM], u16 (&psg)[8]) {
;     if (MODE == 2) {
;       const char* src = img + (size_t)n * IMG;
; #pragma unroll
;       for (int i = 0; i < NIM; i++) if (tid * 16 + 4096 * i < IMG) im[i] = *(const u32x4*)(src + tid * 16 + 4096 * i);
;       {
;         const u32x4 g = *(const u32x4*)(p.P + ((size_t)b * SEQ + n * 16 + (tid >> 4)) * INC + gcol + (tid & 15) * 8);
;     ...
;   if (MODE == 2) {
;     prefetch(0, imA, psg);
;     prefetch(1, imB, psgB);
;     for (int n = 0; n < SEQ / 16; n += 2) {
;       if (n == 62) mid_barrier(p, smem);
;       step(n, imA, psg); step(n + 1, imB, psgB);
;     }
.Lrec_gla_entry:
	v_readlane_b32 s6, v240, 52
	v_readlane_b32 s2, v240, 24
	v_readlane_b32 s3, v240, 25
	s_nop 3
	s_sub_u32 s28, s6, 32
	s_mul_i32 s26, s28, 0x188000
	s_mul_hi_u32 s27, s28, 0x188000
	s_add_u32 s8, s80, s26
	s_addc_u32 s9, s81, s27
	s_lshr_b32 s26, s6, 2
	s_sub_u32 s26, s26, 8
	s_and_b32 s27, s6, 3
	s_mul_i32 s28, s26, 0xe10000
	s_add_u32 s10, s88, s28
	s_addc_u32 s11, s89, 0
	s_lshl_b32 s28, s27, 8
	s_add_u32 s28, s28, 0x1820
	s_add_u32 s10, s10, s28
	s_addc_u32 s11, s11, 0
	s_lshl_b32 s28, s26, 22
	s_add_u32 s12, s2, s28
	s_addc_u32 s13, s3, 0
	s_lshl_b32 s28, s27, 8
	s_add_u32 s28, s28, 0x400
	s_add_u32 s12, s12, s28
	s_addc_u32 s13, s13, 0
	s_sub_u32 s12, s12, 0x10000
	s_subb_u32 s13, s13, 0
	s_mov_b32 s30, 0x3c000000
	s_mov_b32 s4, 1
	s_mov_b32 s36, 0
	v_and_b32_e32 v137, 15, v128
	v_bfe_u32 v139, v128, 4, 2
	v_lshrrev_b32_e32 v142, 6, v128
	v_lshrrev_b32_e32 v178, 4, v128
	v_mul_u32_u24_e32 v202, 144, v137
	v_lshl_add_u32 v144, v139, 3, v202
	v_lshl_add_u32 v202, v142, 5, v137
	v_mul_u32_u24_e32 v202, 40, v202
	v_lshl_add_u32 v145, v139, 3, v202
	v_mul_u32_u24_e32 v202, 40, v137
	v_lshl_add_u32 v146, v139, 3, v202
	v_lshlrev_b32_e32 v147, 4, v139
	v_lshl_add_u32 v148, v142, 6, v147
	v_mul_u32_u24_e32 v202, 0x840, v139
	v_lshl_add_u32 v202, v142, 7, v202
	v_lshl_add_u32 v149, v137, 2, v202
	v_mul_u32_u24_e32 v202, 0x210, v178
	v_lshl_add_u32 v150, v137, 5, v202
	v_lshlrev_b32_e32 v151, 4, v128
	v_add_u32_e32 v152, 0x0, v151
	v_add_u32_e32 v153, 0x1000, v151
	v_add_u32_e32 v154, 0x2000, v151
	v_add_u32_e32 v172, 0x3000, v151
	s_movk_i32 s28, 16
	v_cmp_gt_u32_e64 s[24:25], s28, v128
	s_nop 1
	v_cndmask_b32_e64 v172, 0, v172, s[24:25]
	v_mul_u32_u24_e32 v202, 0x1c20, v178
	v_lshl_add_u32 v173, v137, 4, v202
	v_lshlrev_b32_e32 v202, 11, v178
	v_lshl_add_u32 v174, v137, 4, v202
	v_lshl_add_u32 v202, v142, 5, v137
	s_lshl_b32 s28, s27, 7
	v_add_lshl_u32 v202, s28, v202, 2
	global_load_dword v175, v202, s[64:65]
	global_load_dword v176, v202, s[64:65] offset:64
	v_lshlrev_b32_e32 v203, 2, v139
	v_cmp_gt_u32_e64 s[14:15], v203, v137
	v_add_u32_e32 v184, 1, v203
	v_cmp_gt_u32_e64 s[16:17], v184, v137
	v_add_u32_e32 v184, 2, v203
	v_cmp_gt_u32_e64 s[18:19], v184, v137
	v_add_u32_e32 v184, 3, v203
	v_cmp_gt_u32_e64 s[20:21], v184, v137
	v_cmp_eq_u32_e64 s[22:23], 0, v137
	v_mov_b32_e32 v177, 0x3727c5ac
	v_mov_b32_e32 v48, 0
	v_mov_b32_e32 v49, 0
	v_mov_b32_e32 v50, 0
	v_mov_b32_e32 v51, 0
	v_mov_b32_e32 v52, 0
	v_mov_b32_e32 v53, 0
	v_mov_b32_e32 v54, 0
	v_mov_b32_e32 v55, 0
	v_mov_b32_e32 v56, 0
	v_mov_b32_e32 v57, 0
	v_mov_b32_e32 v58, 0
	v_mov_b32_e32 v59, 0
	v_mov_b32_e32 v60, 0
	v_mov_b32_e32 v61, 0
	v_mov_b32_e32 v62, 0
	v_mov_b32_e32 v63, 0
	v_mov_b32_e32 v64, 0
	v_mov_b32_e32 v65, 0
	v_mov_b32_e32 v66, 0
	v_mov_b32_e32 v67, 0
	v_mov_b32_e32 v68, 0
	v_mov_b32_e32 v69, 0
	v_mov_b32_e32 v70, 0
	v_mov_b32_e32 v71, 0
	v_mov_b32_e32 v72, 0
	v_mov_b32_e32 v73, 0
	v_mov_b32_e32 v74, 0
	v_mov_b32_e32 v75, 0
	v_mov_b32_e32 v76, 0
	v_mov_b32_e32 v77, 0
	v_mov_b32_e32 v78, 0
	v_mov_b32_e32 v79, 0
	global_load_dwordx4 v[0:3], v152, s[8:9]
	global_load_dwordx4 v[4:7], v153, s[8:9]
	global_load_dwordx4 v[8:11], v154, s[8:9]
	global_load_dwordx4 v[12:15], v172, s[8:9]
	s_add_u32 s8, s8, 0x3100
	s_addc_u32 s9, s9, 0
	global_load_dwordx4 v[20:23], v152, s[8:9]
	global_load_dwordx4 v[24:27], v153, s[8:9]
	global_load_dwordx4 v[28:31], v154, s[8:9]
	global_load_dwordx4 v[32:35], v172, s[8:9]
	s_add_u32 s8, s8, 0x3100
	s_addc_u32 s9, s9, 0
	s_waitcnt vmcnt(4)
	ds_write_b128 v151, v[0:3] offset:0
	ds_write_b128 v151, v[4:7] offset:4096
	ds_write_b128 v151, v[8:11] offset:8192
	s_mov_b64 s[26:27], exec
	s_and_b64 exec, exec, s[24:25]
	ds_write_b128 v151, v[12:15] offset:12288
	s_mov_b64 exec, s[26:27]
	global_load_dwordx4 v[0:3], v152, s[8:9]
	global_load_dwordx4 v[4:7], v153, s[8:9]
	global_load_dwordx4 v[8:11], v154, s[8:9]
	global_load_dwordx4 v[12:15], v172, s[8:9]
	s_add_u32 s8, s8, 0x3100
	s_addc_u32 s9, s9, 0
	s_waitcnt lgkmcnt(0)
.Lrec_gla_even:
	s_barrier
	ds_read_b128 v[224:227], v150 offset:39424
	ds_read_b128 v[228:231], v150 offset:39440
	ds_read_b64 v[204:205], v144 offset:2304
	ds_read_b64 v[206:207], v144 offset:2336
	ds_read_b64 v[208:209], v144 offset:0
	ds_read_b64 v[210:211], v144 offset:32
	ds_read_b64 v[116:117], v145 offset:7168
	ds_read_b64 v[118:119], v145 offset:7808
	ds_read_b64 v[212:213], v146 offset:4608
	ds_read_b64 v[214:215], v146 offset:5248
	ds_read_b128 v[216:219], v147 offset:12288
	ds_read_b128 v[220:223], v147 offset:12352
	s_sub_u32 s26, s36, 4
	s_cmp_gt_u32 s26, 120
	s_cselect_b32 s29, 1, 0
	v_cvt_pk_bf16_f32 v120, v48, v49
	v_cvt_pk_bf16_f32 v121, v50, v51
	v_cvt_pk_bf16_f32 v122, v56, v57
	v_cvt_pk_bf16_f32 v123, v58, v59
	v_cvt_pk_bf16_f32 v156, v52, v53
	v_cvt_pk_bf16_f32 v157, v54, v55
	v_cvt_pk_bf16_f32 v158, v60, v61
	v_cvt_pk_bf16_f32 v159, v62, v63
	s_waitcnt lgkmcnt(10)
	s_cmp_lg_u32 s29, 0
	s_cbranch_scc1 .Lrec_gla_p0g_d
	s_waitcnt vmcnt(10)
	s_branch .Lrec_gla_p0g_c

; __device__ __forceinline__ float bf2f(u16 v) { return __uint_as_float(((unsigned)v) << 16); }
; template <int DK, bool HG, int MODE>
; __device__ void recur_unit(const Params& p, char* smem, int b, int h, char* img, int nstart, int nstep, int nend) {
;     ...
;       for (int r = 0; r < 4; r++) {
;         const float rstd = rsqrtf(tot[r] * (1.f / 128.f) + LN_EPS);
;         const int li = (kg * 4 + r) * 136 + w * 32 + l15;
;         sgate[r] = bf2f(GT[li]); sgate[4 + r] = bf2f(GT[li + 16]);
;         OT[li] = f2bf(o[0][r] * rstd * g0 * sgate[r]);
;         OT[li + 16] = f2bf(o[1][r] * rstd * g1 * sgate[4 + r]);
;       }
;     }
;     __syncthreads();
;     *(u32x4*)(p.O + ((size_t)b * SEQ + n * 16 + (tid >> 4)) * DM + ocol + (tid & 15) * 8) = *(const u32x4*)&OT[(tid >> 4) * 136 + (tid & 15) * 8];
.Lrec_gla_p0g_c:
	v_lshlrev_b32_e32 v232, 16, v40
	v_and_b32_e32 v233, 0xffff0000, v40
	v_lshlrev_b32_e32 v234, 16, v41
	v_and_b32_e32 v235, 0xffff0000, v41
	v_lshlrev_b32_e32 v236, 16, v42
	v_and_b32_e32 v237, 0xffff0000, v42
	v_lshlrev_b32_e32 v238, 16, v43
	v_and_b32_e32 v239, 0xffff0000, v43
	v_pk_mul_f32 v[224:225], v[224:225], v[232:233]
	v_pk_mul_f32 v[226:227], v[226:227], v[234:235]
	v_pk_mul_f32 v[228:229], v[228:229], v[236:237]
	v_pk_mul_f32 v[230:231], v[230:231], v[238:239]
	v_cvt_pk_bf16_f32 v232, v224, v225
	v_cvt_pk_bf16_f32 v233, v226, v227
	v_cvt_pk_bf16_f32 v234, v228, v229
	v_cvt_pk_bf16_f32 v235, v230, v231
	s_cmp_lt_u32 s36, 2
	s_cbranch_scc1 .Lrec_gla_p0_nost
	global_store_dwordx4 v174, v[232:235], s[12:13]
; #define STAGE() do { } while (0)
; template <int DK, bool HG, int MODE>
; __device__ void recur_unit(const Params& p, char* smem, int b, int h, char* img, int nstart, int nstep, int nend) {
;     ...
;     f32x4 sc = f32x4{0, 0, 0, 0};
;     bf16x8 qf[NKS];
; #pragma unroll
;     for (int st = 0; st < NKS; st++) {
;       bf16x4 q0 = *(const bf16x4*)&Qt[l15 * LQ + 32 * st + kg * 4];
;       bf16x4 q1 = *(const bf16x4*)&Qt[l15 * LQ + 32 * st + 16 + kg * 4];
;       bf16x4 c0 = *(const bf16x4*)&Kt[l15 * LQ + 32 * st + kg * 4];
;       bf16x4 c1 = *(const bf16x4*)&Kt[l15 * LQ + 32 * st + 16 + kg * 4];
;       qf[st] = bf16x8{q0[0], q0[1], q0[2], q0[3], q1[0], q1[1], q1[2], q1[3]};
;       bf16x8 kf = bf16x8{c0[0], c0[1], c0[2], c0[3], c1[0], c1[1], c1[2], c1[3]};
;       sc = __builtin_amdgcn_mfma_f32_16x16x32_bf16(kf, qf[st], sc, 0, 0, 0);
;     }
;     STAGE();
; #pragma unroll
;     for (int r = 0; r < 4; r++) if (kg * 4 + r > l15) sc[r] = 0.f;
;     bf16x4 pA;
;     {
;       unsigned a = pack2(sc[0], sc[1]), c = pack2(sc[2], sc[3]);
;       pA = bf16x4{(short)(a & 0xffff), (short)(a >> 16), (short)(c & 0xffff), (short)(c >> 16)};
;     }
;     bf16x4 vf[2];
;     f32x4 o[2], oin[2];
;     bf16x8 sbv[2][NKS];
; #pragma unroll
;     for (int vt = 0; vt < 2; vt++) {
;       vf[vt] = *(const bf16x4*)&VT[(w * 32 + vt * 16 + l15) * 20 + kg * 4];
; #pragma unroll
;       for (int st = 0; st < NKS; st++) {
;         unsigned s0 = pack2(S[2 * st][vt][0], S[2 * st][vt][1]), s1 = pack2(S[2 * st][vt][2], S[2 * st][vt][3]);
;         unsigned s2 = pack2(S[2 * st + 1][vt][0], S[2 * st + 1][vt][1]), s3 = pack2(S[2 * st + 1][vt][2], S[2 * st + 1][vt][3]);
;         sbv[vt][st] = bf16x8{(short)(s0 & 0xffff), (short)(s0 >> 16), (short)(s1 & 0xffff), (short)(s1 >> 16),
;                            (short)(s2 & 0xffff), (short)(s2 >> 16), (short)(s3 & 0xffff), (short)(s3 >> 16)};
;       }
;     }
;     STAGE();
; #pragma unroll
;     for (int vt = 0; vt < 2; vt++) {
;       o[vt] = __builtin_amdgcn_mfma_f32_16x16x16bf16_1k(pA, vf[vt], f32x4{0, 0, 0, 0}, 0, 0, 0);
;       oin[vt] = f32x4{0, 0, 0, 0};
; #pragma unroll
;       for (int st = 0; st < NKS; st++) oin[vt] = __builtin_amdgcn_mfma_f32_16x16x32_bf16(qf[st], sbv[vt][st], oin[vt], 0, 0, 0);
;     }
;     STAGE();
;     bf16x4 khf[NKT];
; #pragma unroll
;     for (int kt2 = 0; kt2 < NKT; kt2++) {
.Lrec_gla_p0_nost:
	global_load_dwordx4 v[40:43], v173, s[10:11]
	s_add_u32 s10, s10, 0x1c200
	s_addc_u32 s11, s11, 0
	s_add_u32 s12, s12, 0x8000
	s_addc_u32 s13, s13, 0
	ds_read_b64 v[224:225], v144 offset:2368
	ds_read_b64 v[226:227], v144 offset:2400
	ds_read_b64 v[228:229], v144 offset:64
	ds_read_b64 v[230:231], v144 offset:96
	ds_read_b64 v[232:233], v146 offset:5888
	ds_read_b64 v[234:235], v146 offset:6528
	ds_read_b128 v[236:239], v147 offset:12416
	ds_read_b128 v[112:115], v147 offset:12480
	s_waitcnt lgkmcnt(14)
	v_mfma_f32_16x16x32_bf16 a[0:3], v[204:207], v[208:211], 0
	v_mfma_f32_16x16x32_bf16 a[4:7], v[208:211], v[120:123], 0
	v_mfma_f32_16x16x32_bf16 a[8:11], v[208:211], v[156:159], 0
	s_waitcnt lgkmcnt(8)
	v_pk_mul_f32 v[48:49], v[48:49], v[216:217]
	v_pk_mul_f32 v[50:51], v[50:51], v[218:219]
	v_pk_mul_f32 v[52:53], v[52:53], v[216:217]
	v_pk_mul_f32 v[54:55], v[54:55], v[218:219]
	v_mfma_f32_16x16x16_bf16 v[48:51], v[212:213], v[116:117], v[48:51]
	v_pk_mul_f32 v[56:57], v[56:57], v[220:221]
	v_pk_mul_f32 v[58:59], v[58:59], v[222:223]
	v_mfma_f32_16x16x16_bf16 v[52:55], v[212:213], v[118:119], v[52:55]
	v_pk_mul_f32 v[60:61], v[60:61], v[220:221]
	v_pk_mul_f32 v[62:63], v[62:63], v[222:223]
	v_mfma_f32_16x16x16_bf16 v[56:59], v[214:215], v[116:117], v[56:59]
	v_cvt_pk_bf16_f32 v120, v64, v65
	v_cvt_pk_bf16_f32 v121, v66, v67
	v_mfma_f32_16x16x16_bf16 v[60:63], v[214:215], v[118:119], v[60:63]
	v_cvt_pk_bf16_f32 v122, v72, v73
	v_cvt_pk_bf16_f32 v123, v74, v75
	v_cvt_pk_bf16_f32 v156, v68, v69
	v_cvt_pk_bf16_f32 v157, v70, v71
	v_cvt_pk_bf16_f32 v158, v76, v77
	v_cvt_pk_bf16_f32 v159, v78, v79
	s_waitcnt lgkmcnt(4)
	v_mfma_f32_16x16x32_bf16 a[0:3], v[224:227], v[228:231], a[0:3]
	v_mfma_f32_16x16x32_bf16 a[4:7], v[228:231], v[120:123], a[4:7]
	v_mfma_f32_16x16x32_bf16 a[8:11], v[228:231], v[156:159], a[8:11]
	s_waitcnt lgkmcnt(0)
	v_pk_mul_f32 v[64:65], v[64:65], v[236:237]
	v_pk_mul_f32 v[66:67], v[66:67], v[238:239]
	v_pk_mul_f32 v[68:69], v[68:69], v[236:237]
	v_pk_mul_f32 v[70:71], v[70:71], v[238:239]
	v_mfma_f32_16x16x16_bf16 v[64:67], v[232:233], v[116:117], v[64:67]
	v_pk_mul_f32 v[72:73], v[72:73], v[112:113]
	v_pk_mul_f32 v[74:75], v[74:75], v[114:115]
	v_mfma_f32_16x16x16_bf16 v[68:71], v[232:233], v[118:119], v[68:71]
	v_pk_mul_f32 v[76:77], v[76:77], v[112:113]
	v_pk_mul_f32 v[78:79], v[78:79], v[114:115]
	v_mfma_f32_16x16x16_bf16 v[72:75], v[234:235], v[116:117], v[72:75]
	s_nop 1
	v_mfma_f32_16x16x16_bf16 v[76:79], v[234:235], v[118:119], v[76:79]
	ds_read_b128 v[204:207], v147 offset:39168
	ds_read_b128 v[208:211], v147 offset:39232
	ds_read_b128 v[212:215], v147 offset:39296
	ds_read_b128 v[216:219], v147 offset:39360
	v_accvgpr_read_b32 v224, a0
	v_accvgpr_read_b32 v225, a1
	v_accvgpr_read_b32 v226, a2
	v_accvgpr_read_b32 v227, a3
	v_accvgpr_read_b32 v228, a4
	v_accvgpr_read_b32 v229, a5
	v_accvgpr_read_b32 v230, a6
	v_accvgpr_read_b32 v231, a7
	v_accvgpr_read_b32 v232, a8
	v_accvgpr_read_b32 v233, a9
	v_accvgpr_read_b32 v234, a10
	v_accvgpr_read_b32 v235, a11
	v_cndmask_b32_e64 v224, v224, 0, s[14:15]
	v_cndmask_b32_e64 v225, v225, 0, s[16:17]
	v_cndmask_b32_e64 v226, v226, 0, s[18:19]
	v_cndmask_b32_e64 v227, v227, 0, s[20:21]
	v_cvt_pk_bf16_f32 v140, v224, v225
	v_cvt_pk_bf16_f32 v141, v226, v227
	s_nop 1
	v_mfma_f32_16x16x16_bf16 v[186:189], v[140:141], v[116:117], 0
	v_mfma_f32_16x16x16_bf16 v[190:193], v[140:141], v[118:119], 0
	s_nop 7
	s_nop 1
	v_pk_add_f32 v[186:187], v[186:187], v[228:229]
	v_pk_add_f32 v[188:189], v[188:189], v[230:231]
	v_pk_add_f32 v[190:191], v[190:191], v[232:233]
	v_pk_add_f32 v[192:193], v[192:193], v[234:235]
	v_pk_mul_f32 v[236:237], v[190:191], v[190:191]
	v_pk_mul_f32 v[238:239], v[192:193], v[192:193]
	v_pk_fma_f32 v[112:113], v[186:187], v[186:187], v[236:237]
	v_pk_fma_f32 v[114:115], v[188:189], v[188:189], v[238:239]
	s_nop 1
	v_add_f32_dpp v112, v112, v112 row_ror:8 row_mask:0xf bank_mask:0xf
	v_add_f32_dpp v113, v113, v113 row_ror:8 row_mask:0xf bank_mask:0xf
	v_add_f32_dpp v114, v114, v114 row_ror:8 row_mask:0xf bank_mask:0xf
	v_add_f32_dpp v115, v115, v115 row_ror:8 row_mask:0xf bank_mask:0xf
	v_add_f32_dpp v112, v112, v112 row_ror:4 row_mask:0xf bank_mask:0xf
	v_add_f32_dpp v113, v113, v113 row_ror:4 row_mask:0xf bank_mask:0xf
	v_add_f32_dpp v114, v114, v114 row_ror:4 row_mask:0xf bank_mask:0xf
	v_add_f32_dpp v115, v115, v115 row_ror:4 row_mask:0xf bank_mask:0xf
	v_add_f32_dpp v112, v112, v112 row_ror:2 row_mask:0xf bank_mask:0xf
	v_add_f32_dpp v113, v113, v113 row_ror:2 row_mask:0xf bank_mask:0xf
	v_add_f32_dpp v114, v114, v114 row_ror:2 row_mask:0xf bank_mask:0xf
	v_add_f32_dpp v115, v115, v115 row_ror:2 row_mask:0xf bank_mask:0xf
	v_add_f32_dpp v112, v112, v112 row_ror:1 row_mask:0xf bank_mask:0xf
	v_add_f32_dpp v113, v113, v113 row_ror:1 row_mask:0xf bank_mask:0xf
	v_add_f32_dpp v114, v114, v114 row_ror:1 row_mask:0xf bank_mask:0xf
	v_add_f32_dpp v115, v115, v115 row_ror:1 row_mask:0xf bank_mask:0xf
	s_mov_b64 s[26:27], exec
	s_and_b64 exec, exec, s[22:23]
	ds_write_b128 v148, v[112:115] offset:38912
	s_mov_b64 exec, s[26:27]
	s_waitcnt lgkmcnt(1)
	v_pk_add_f32 v[220:221], v[204:205], v[208:209]
	v_pk_add_f32 v[222:223], v[206:207], v[210:211]
	v_pk_add_f32 v[220:221], v[220:221], v[212:213]
	v_pk_add_f32 v[222:223], v[222:223], v[214:215]
	v_pk_add_f32 v[220:221], v[220:221], v[216:217]
	v_pk_add_f32 v[222:223], v[222:223], v[218:219]
	v_fma_f32 v220, v220, s30, v177
	v_fma_f32 v221, v221, s30, v177
	v_fma_f32 v222, v222, s30, v177
	v_fma_f32 v223, v223, s30, v177
	v_rsq_f32_e32 v220, v220
	v_rsq_f32_e32 v221, v221
	v_rsq_f32_e32 v222, v222
	v_rsq_f32_e32 v223, v223
	s_nop 0
	v_mul_f32_e32 v204, v194, v220
	v_mul_f32_e32 v205, v195, v221
	v_mul_f32_e32 v206, v196, v222
	v_mul_f32_e32 v207, v197, v223
	v_mul_f32_e32 v208, v198, v220
	v_mul_f32_e32 v209, v199, v221
	v_mul_f32_e32 v210, v200, v222
	v_mul_f32_e32 v211, v201, v223
	v_mul_f32_e32 v204, v175, v204
	v_mul_f32_e32 v205, v175, v205
	v_mul_f32_e32 v206, v175, v206
	v_mul_f32_e32 v207, v175, v207
	v_mul_f32_e32 v208, v176, v208
	v_mul_f32_e32 v209, v176, v209
	v_mul_f32_e32 v210, v176, v210
	v_mul_f32_e32 v211, v176, v211
	ds_write_b32 v149, v204 offset:47872
	ds_write_b32 v149, v205 offset:48400
	ds_write_b32 v149, v206 offset:48928
	ds_write_b32 v149, v207 offset:49456
	ds_write_b32 v149, v208 offset:47936
	ds_write_b32 v149, v209 offset:48464
	ds_write_b32 v149, v210 offset:48992
	ds_write_b32 v149, v211 offset:49520
	s_cmp_lg_u32 s29, 0
	s_cbranch_scc1 .Lrec_gla_p0w_d
	s_waitcnt vmcnt(8)
	s_branch .Lrec_gla_p0w_c

; template <int DK, bool HG, int MODE>
; __device__ void recur_unit(const Params& p, char* smem, int b, int h, char* img, int nstart, int nstep, int nend) {
;     ...
;   auto step = [&](int n, u32x4 (&im)[NIM], u16 (&psg)[8]) {
;     float sgate[8];
;     if (MODE == 2) {
; #pragma unroll
;       for (int i = 0; i < NIM; i++) if (tid * 16 + 4096 * i < IMG) *(u32x4*)(smem + tid * 16 + 4096 * i) = im[i];
;       {
;         u32x4 g;
;         g[0] = (unsigned)psg[0] | ((unsigned)psg[1] << 16); g[1] = (unsigned)psg[2] | ((unsigned)psg[3] << 16);
;         g[2] = (unsigned)psg[4] | ((unsigned)psg[5] << 16); g[3] = (unsigned)psg[6] | ((unsigned)psg[7] << 16);
;         *(u32x4*)&GT[(tid >> 4) * 136 + (tid & 15) * 8] = g;
;       }
;       __builtin_amdgcn_sched_barrier(0);
;       if (n + PFD * nstep < nend) prefetch(n + PFD * nstep, im, psg);
;       __builtin_amdgcn_sched_barrier(0);
;     ...
;     for (int n = 0; n < SEQ / 16; n += 2) {
;       if (n == 62) mid_barrier(p, smem);
;       step(n, imA, psg); step(n + 1, imB, psgB);
.Lrec_gla_p0w_c:
	ds_write_b128 v151, v[20:23] offset:12544
	ds_write_b128 v151, v[24:27] offset:16640
	ds_write_b128 v151, v[28:31] offset:20736
	s_mov_b64 s[26:27], exec
	s_and_b64 exec, exec, s[24:25]
	ds_write_b128 v151, v[32:35] offset:24832
	s_mov_b64 exec, s[26:27]
	s_cmp_gt_u32 s36, 124
	s_cbranch_scc1 .Lrec_gla_p0_nol
	global_load_dwordx4 v[20:23], v152, s[8:9]
	global_load_dwordx4 v[24:27], v153, s[8:9]
	global_load_dwordx4 v[28:31], v154, s[8:9]
	global_load_dwordx4 v[32:35], v172, s[8:9]
	s_add_u32 s8, s8, 0x3100
	s_addc_u32 s9, s9, 0
.Lrec_gla_p0_nol:
	s_add_u32 s36, s36, 1
	s_waitcnt lgkmcnt(0)
	s_cmp_eq_u32 s36, 61
	s_cbranch_scc1 .LBB0_698
	s_barrier
.Lrec_gla_midret:
	ds_read_b128 v[224:227], v150 offset:47872
	ds_read_b128 v[228:231], v150 offset:47888
	ds_read_b64 v[204:205], v144 offset:14848
	ds_read_b64 v[206:207], v144 offset:14880
	ds_read_b64 v[208:209], v144 offset:12544
	ds_read_b64 v[210:211], v144 offset:12576
	ds_read_b64 v[116:117], v145 offset:19712
	ds_read_b64 v[118:119], v145 offset:20352
	ds_read_b64 v[212:213], v146 offset:17152
	ds_read_b64 v[214:215], v146 offset:17792
	ds_read_b128 v[216:219], v147 offset:24832
	ds_read_b128 v[220:223], v147 offset:24896
	s_sub_u32 s26, s36, 4
	s_cmp_gt_u32 s26, 120
	s_cselect_b32 s29, 1, 0
	v_cvt_pk_bf16_f32 v120, v48, v49
	v_cvt_pk_bf16_f32 v121, v50, v51
	v_cvt_pk_bf16_f32 v122, v56, v57
	v_cvt_pk_bf16_f32 v123, v58, v59
	v_cvt_pk_bf16_f32 v156, v52, v53
	v_cvt_pk_bf16_f32 v157, v54, v55
	v_cvt_pk_bf16_f32 v158, v60, v61
	v_cvt_pk_bf16_f32 v159, v62, v63
	s_waitcnt lgkmcnt(10)
	s_cmp_lg_u32 s29, 0
	s_cbranch_scc1 .Lrec_gla_p1g_d
	s_waitcnt vmcnt(10)
	s_branch .Lrec_gla_p1g_c

; __device__ __forceinline__ float bf2f(u16 v) { return __uint_as_float(((unsigned)v) << 16); }
; template <int DK, bool HG, int MODE>
; __device__ void recur_unit(const Params& p, char* smem, int b, int h, char* img, int nstart, int nstep, int nend) {
;     ...
;       for (int r = 0; r < 4; r++) {
;         const float rstd = rsqrtf(tot[r] * (1.f / 128.f) + LN_EPS);
;         const int li = (kg * 4 + r) * 136 + w * 32 + l15;
;         sgate[r] = bf2f(GT[li]); sgate[4 + r] = bf2f(GT[li + 16]);
;         OT[li] = f2bf(o[0][r] * rstd * g0 * sgate[r]);
;         OT[li + 16] = f2bf(o[1][r] * rstd * g1 * sgate[4 + r]);
;       }
;     }
;     __syncthreads();
;     *(u32x4*)(p.O + ((size_t)b * SEQ + n * 16 + (tid >> 4)) * DM + ocol + (tid & 15) * 8) = *(const u32x4*)&OT[(tid >> 4) * 136 + (tid & 15) * 8];
.Lrec_gla_p1g_c:
	v_lshlrev_b32_e32 v232, 16, v44
	v_and_b32_e32 v233, 0xffff0000, v44
	v_lshlrev_b32_e32 v234, 16, v45
	v_and_b32_e32 v235, 0xffff0000, v45
	v_lshlrev_b32_e32 v236, 16, v46
	v_and_b32_e32 v237, 0xffff0000, v46
	v_lshlrev_b32_e32 v238, 16, v47
	v_and_b32_e32 v239, 0xffff0000, v47
	v_pk_mul_f32 v[224:225], v[224:225], v[232:233]
	v_pk_mul_f32 v[226:227], v[226:227], v[234:235]
	v_pk_mul_f32 v[228:229], v[228:229], v[236:237]
	v_pk_mul_f32 v[230:231], v[230:231], v[238:239]
	v_cvt_pk_bf16_f32 v232, v224, v225
	v_cvt_pk_bf16_f32 v233, v226, v227
	v_cvt_pk_bf16_f32 v234, v228, v229
	v_cvt_pk_bf16_f32 v235, v230, v231
	s_cmp_lt_u32 s36, 2
	s_cbranch_scc1 .Lrec_gla_p1_nost
	global_store_dwordx4 v174, v[232:235], s[12:13]
; #define STAGE() do { } while (0)
; template <int DK, bool HG, int MODE>
; __device__ void recur_unit(const Params& p, char* smem, int b, int h, char* img, int nstart, int nstep, int nend) {
;     ...
;     f32x4 sc = f32x4{0, 0, 0, 0};
;     bf16x8 qf[NKS];
; #pragma unroll
;     for (int st = 0; st < NKS; st++) {
;       bf16x4 q0 = *(const bf16x4*)&Qt[l15 * LQ + 32 * st + kg * 4];
;       bf16x4 q1 = *(const bf16x4*)&Qt[l15 * LQ + 32 * st + 16 + kg * 4];
;       bf16x4 c0 = *(const bf16x4*)&Kt[l15 * LQ + 32 * st + kg * 4];
;       bf16x4 c1 = *(const bf16x4*)&Kt[l15 * LQ + 32 * st + 16 + kg * 4];
;       qf[st] = bf16x8{q0[0], q0[1], q0[2], q0[3], q1[0], q1[1], q1[2], q1[3]};
;       bf16x8 kf = bf16x8{c0[0], c0[1], c0[2], c0[3], c1[0], c1[1], c1[2], c1[3]};
;       sc = __builtin_amdgcn_mfma_f32_16x16x32_bf16(kf, qf[st], sc, 0, 0, 0);
;     }
;     STAGE();
; #pragma unroll
;     for (int r = 0; r < 4; r++) if (kg * 4 + r > l15) sc[r] = 0.f;
;     bf16x4 pA;
;     {
;       unsigned a = pack2(sc[0], sc[1]), c = pack2(sc[2], sc[3]);
;       pA = bf16x4{(short)(a & 0xffff), (short)(a >> 16), (short)(c & 0xffff), (short)(c >> 16)};
;     }
;     bf16x4 vf[2];
;     f32x4 o[2], oin[2];
;     bf16x8 sbv[2][NKS];
; #pragma unroll
;     for (int vt = 0; vt < 2; vt++) {
;       vf[vt] = *(const bf16x4*)&VT[(w * 32 + vt * 16 + l15) * 20 + kg * 4];
; #pragma unroll
;       for (int st = 0; st < NKS; st++) {
;         unsigned s0 = pack2(S[2 * st][vt][0], S[2 * st][vt][1]), s1 = pack2(S[2 * st][vt][2], S[2 * st][vt][3]);
;         unsigned s2 = pack2(S[2 * st + 1][vt][0], S[2 * st + 1][vt][1]), s3 = pack2(S[2 * st + 1][vt][2], S[2 * st + 1][vt][3]);
;         sbv[vt][st] = bf16x8{(short)(s0 & 0xffff), (short)(s0 >> 16), (short)(s1 & 0xffff), (short)(s1 >> 16),
;                            (short)(s2 & 0xffff), (short)(s2 >> 16), (short)(s3 & 0xffff), (short)(s3 >> 16)};
;       }
;     }
;     STAGE();
; #pragma unroll
;     for (int vt = 0; vt < 2; vt++) {
;       o[vt] = __builtin_amdgcn_mfma_f32_16x16x16bf16_1k(pA, vf[vt], f32x4{0, 0, 0, 0}, 0, 0, 0);
;       oin[vt] = f32x4{0, 0, 0, 0};
; #pragma unroll
;       for (int st = 0; st < NKS; st++) oin[vt] = __builtin_amdgcn_mfma_f32_16x16x32_bf16(qf[st], sbv[vt][st], oin[vt], 0, 0, 0);
;     }
;     STAGE();
;     bf16x4 khf[NKT];
; #pragma unroll
;     for (int kt2 = 0; kt2 < NKT; kt2++) {
.Lrec_gla_p1_nost:
	global_load_dwordx4 v[44:47], v173, s[10:11]
	s_add_u32 s10, s10, 0x1c200
	s_addc_u32 s11, s11, 0
	s_add_u32 s12, s12, 0x8000
	s_addc_u32 s13, s13, 0
	ds_read_b64 v[224:225], v144 offset:14912
	ds_read_b64 v[226:227], v144 offset:14944
	ds_read_b64 v[228:229], v144 offset:12608
	ds_read_b64 v[230:231], v144 offset:12640
	ds_read_b64 v[232:233], v146 offset:18432
	ds_read_b64 v[234:235], v146 offset:19072
	ds_read_b128 v[236:239], v147 offset:24960
	ds_read_b128 v[112:115], v147 offset:25024
	s_waitcnt lgkmcnt(14)
	v_mfma_f32_16x16x32_bf16 a[0:3], v[204:207], v[208:211], 0
	v_mfma_f32_16x16x32_bf16 a[4:7], v[208:211], v[120:123], 0
	v_mfma_f32_16x16x32_bf16 a[8:11], v[208:211], v[156:159], 0
	s_waitcnt lgkmcnt(8)
	v_pk_mul_f32 v[48:49], v[48:49], v[216:217]
	v_pk_mul_f32 v[50:51], v[50:51], v[218:219]
	v_pk_mul_f32 v[52:53], v[52:53], v[216:217]
	v_pk_mul_f32 v[54:55], v[54:55], v[218:219]
	v_mfma_f32_16x16x16_bf16 v[48:51], v[212:213], v[116:117], v[48:51]
	v_pk_mul_f32 v[56:57], v[56:57], v[220:221]
	v_pk_mul_f32 v[58:59], v[58:59], v[222:223]
	v_mfma_f32_16x16x16_bf16 v[52:55], v[212:213], v[118:119], v[52:55]
	v_pk_mul_f32 v[60:61], v[60:61], v[220:221]
	v_pk_mul_f32 v[62:63], v[62:63], v[222:223]
	v_mfma_f32_16x16x16_bf16 v[56:59], v[214:215], v[116:117], v[56:59]
	v_cvt_pk_bf16_f32 v120, v64, v65
	v_cvt_pk_bf16_f32 v121, v66, v67
	v_mfma_f32_16x16x16_bf16 v[60:63], v[214:215], v[118:119], v[60:63]
	v_cvt_pk_bf16_f32 v122, v72, v73
	v_cvt_pk_bf16_f32 v123, v74, v75
	v_cvt_pk_bf16_f32 v156, v68, v69
	v_cvt_pk_bf16_f32 v157, v70, v71
	v_cvt_pk_bf16_f32 v158, v76, v77
	v_cvt_pk_bf16_f32 v159, v78, v79
	s_waitcnt lgkmcnt(4)
	v_mfma_f32_16x16x32_bf16 a[0:3], v[224:227], v[228:231], a[0:3]
	v_mfma_f32_16x16x32_bf16 a[4:7], v[228:231], v[120:123], a[4:7]
	v_mfma_f32_16x16x32_bf16 a[8:11], v[228:231], v[156:159], a[8:11]
	s_waitcnt lgkmcnt(0)
	v_pk_mul_f32 v[64:65], v[64:65], v[236:237]
	v_pk_mul_f32 v[66:67], v[66:67], v[238:239]
	v_pk_mul_f32 v[68:69], v[68:69], v[236:237]
	v_pk_mul_f32 v[70:71], v[70:71], v[238:239]
	v_mfma_f32_16x16x16_bf16 v[64:67], v[232:233], v[116:117], v[64:67]
	v_pk_mul_f32 v[72:73], v[72:73], v[112:113]
	v_pk_mul_f32 v[74:75], v[74:75], v[114:115]
	v_mfma_f32_16x16x16_bf16 v[68:71], v[232:233], v[118:119], v[68:71]
	v_pk_mul_f32 v[76:77], v[76:77], v[112:113]
	v_pk_mul_f32 v[78:79], v[78:79], v[114:115]
	v_mfma_f32_16x16x16_bf16 v[72:75], v[234:235], v[116:117], v[72:75]
	s_nop 1
	v_mfma_f32_16x16x16_bf16 v[76:79], v[234:235], v[118:119], v[76:79]
	ds_read_b128 v[204:207], v147 offset:38912
	ds_read_b128 v[208:211], v147 offset:38976
	ds_read_b128 v[212:215], v147 offset:39040
	ds_read_b128 v[216:219], v147 offset:39104
	v_accvgpr_read_b32 v224, a0
	v_accvgpr_read_b32 v225, a1
	v_accvgpr_read_b32 v226, a2
	v_accvgpr_read_b32 v227, a3
	v_accvgpr_read_b32 v228, a4
	v_accvgpr_read_b32 v229, a5
	v_accvgpr_read_b32 v230, a6
	v_accvgpr_read_b32 v231, a7
	v_accvgpr_read_b32 v232, a8
	v_accvgpr_read_b32 v233, a9
	v_accvgpr_read_b32 v234, a10
	v_accvgpr_read_b32 v235, a11
	v_cndmask_b32_e64 v224, v224, 0, s[14:15]
	v_cndmask_b32_e64 v225, v225, 0, s[16:17]
	v_cndmask_b32_e64 v226, v226, 0, s[18:19]
	v_cndmask_b32_e64 v227, v227, 0, s[20:21]
	v_cvt_pk_bf16_f32 v140, v224, v225
	v_cvt_pk_bf16_f32 v141, v226, v227
	s_nop 1
	v_mfma_f32_16x16x16_bf16 v[194:197], v[140:141], v[116:117], 0
	v_mfma_f32_16x16x16_bf16 v[198:201], v[140:141], v[118:119], 0
	s_nop 7
	s_nop 1
	v_pk_add_f32 v[194:195], v[194:195], v[228:229]
	v_pk_add_f32 v[196:197], v[196:197], v[230:231]
	v_pk_add_f32 v[198:199], v[198:199], v[232:233]
	v_pk_add_f32 v[200:201], v[200:201], v[234:235]
	v_pk_mul_f32 v[236:237], v[198:199], v[198:199]
	v_pk_mul_f32 v[238:239], v[200:201], v[200:201]
	v_pk_fma_f32 v[112:113], v[194:195], v[194:195], v[236:237]
	v_pk_fma_f32 v[114:115], v[196:197], v[196:197], v[238:239]
	s_nop 1
	v_add_f32_dpp v112, v112, v112 row_ror:8 row_mask:0xf bank_mask:0xf
	v_add_f32_dpp v113, v113, v113 row_ror:8 row_mask:0xf bank_mask:0xf
	v_add_f32_dpp v114, v114, v114 row_ror:8 row_mask:0xf bank_mask:0xf
	v_add_f32_dpp v115, v115, v115 row_ror:8 row_mask:0xf bank_mask:0xf
	v_add_f32_dpp v112, v112, v112 row_ror:4 row_mask:0xf bank_mask:0xf
	v_add_f32_dpp v113, v113, v113 row_ror:4 row_mask:0xf bank_mask:0xf
	v_add_f32_dpp v114, v114, v114 row_ror:4 row_mask:0xf bank_mask:0xf
	v_add_f32_dpp v115, v115, v115 row_ror:4 row_mask:0xf bank_mask:0xf
	v_add_f32_dpp v112, v112, v112 row_ror:2 row_mask:0xf bank_mask:0xf
	v_add_f32_dpp v113, v113, v113 row_ror:2 row_mask:0xf bank_mask:0xf
	v_add_f32_dpp v114, v114, v114 row_ror:2 row_mask:0xf bank_mask:0xf
	v_add_f32_dpp v115, v115, v115 row_ror:2 row_mask:0xf bank_mask:0xf
	v_add_f32_dpp v112, v112, v112 row_ror:1 row_mask:0xf bank_mask:0xf
	v_add_f32_dpp v113, v113, v113 row_ror:1 row_mask:0xf bank_mask:0xf
	v_add_f32_dpp v114, v114, v114 row_ror:1 row_mask:0xf bank_mask:0xf
	v_add_f32_dpp v115, v115, v115 row_ror:1 row_mask:0xf bank_mask:0xf
	s_mov_b64 s[26:27], exec
	s_and_b64 exec, exec, s[22:23]
	ds_write_b128 v148, v[112:115] offset:39168
	s_mov_b64 exec, s[26:27]
	s_waitcnt lgkmcnt(1)
	v_pk_add_f32 v[220:221], v[204:205], v[208:209]
	v_pk_add_f32 v[222:223], v[206:207], v[210:211]
	v_pk_add_f32 v[220:221], v[220:221], v[212:213]
	v_pk_add_f32 v[222:223], v[222:223], v[214:215]
	v_pk_add_f32 v[220:221], v[220:221], v[216:217]
	v_pk_add_f32 v[222:223], v[222:223], v[218:219]
	v_fma_f32 v220, v220, s30, v177
	v_fma_f32 v221, v221, s30, v177
	v_fma_f32 v222, v222, s30, v177
	v_fma_f32 v223, v223, s30, v177
	v_rsq_f32_e32 v220, v220
	v_rsq_f32_e32 v221, v221
	v_rsq_f32_e32 v222, v222
	v_rsq_f32_e32 v223, v223
	s_nop 0
	v_mul_f32_e32 v204, v186, v220
	v_mul_f32_e32 v205, v187, v221
	v_mul_f32_e32 v206, v188, v222
	v_mul_f32_e32 v207, v189, v223
	v_mul_f32_e32 v208, v190, v220
	v_mul_f32_e32 v209, v191, v221
	v_mul_f32_e32 v210, v192, v222
	v_mul_f32_e32 v211, v193, v223
	v_mul_f32_e32 v204, v175, v204
	v_mul_f32_e32 v205, v175, v205
	v_mul_f32_e32 v206, v175, v206
	v_mul_f32_e32 v207, v175, v207
	v_mul_f32_e32 v208, v176, v208
	v_mul_f32_e32 v209, v176, v209
	v_mul_f32_e32 v210, v176, v210
	v_mul_f32_e32 v211, v176, v211
	ds_write_b32 v149, v204 offset:39424
	ds_write_b32 v149, v205 offset:39952
	ds_write_b32 v149, v206 offset:40480
	ds_write_b32 v149, v207 offset:41008
	ds_write_b32 v149, v208 offset:39488
	ds_write_b32 v149, v209 offset:40016
	ds_write_b32 v149, v210 offset:40544
	ds_write_b32 v149, v211 offset:41072
	s_cmp_lg_u32 s29, 0
	s_cbranch_scc1 .Lrec_gla_p1w_d
	s_waitcnt vmcnt(8)
	s_branch .Lrec_gla_p1w_c

; __device__ __forceinline__ float bf2f(u16 v) { return __uint_as_float(((unsigned)v) << 16); }
; template <int DK, bool HG, int MODE>
; __device__ void recur_unit(const Params& p, char* smem, int b, int h, char* img, int nstart, int nstep, int nend) {
;     ...
;     float ss[4];
; #pragma unroll
;     for (int r = 0; r < 4; r++) {
;       o[0][r] += oin[0][r]; o[1][r] += oin[1][r];
;       float s = o[0][r] * o[0][r] + o[1][r] * o[1][r];
;       s = dpp_row_sum(s);
;       ss[r] = s;
;     }
;     if (l15 == 0) *(float4*)&SS[w * 16 + kg * 4] = make_float4(ss[0], ss[1], ss[2], ss[3]);
;     __syncthreads();
;     {
;       float4 a0 = *(const float4*)&SS[0 * 16 + kg * 4], a1 = *(const float4*)&SS[1 * 16 + kg * 4];
;       float4 a2 = *(const float4*)&SS[2 * 16 + kg * 4], a3 = *(const float4*)&SS[3 * 16 + kg * 4];
;       float tot[4] = {a0.x + a1.x + a2.x + a3.x, a0.y + a1.y + a2.y + a3.y, a0.z + a1.z + a2.z + a3.z, a0.w + a1.w + a2.w + a3.w};
; #pragma unroll
;       for (int r = 0; r < 4; r++) {
;         const float rstd = rsqrtf(tot[r] * (1.f / 128.f) + LN_EPS);
;         const int li = (kg * 4 + r) * 136 + w * 32 + l15;
;         sgate[r] = bf2f(GT[li]); sgate[4 + r] = bf2f(GT[li + 16]);
;         OT[li] = f2bf(o[0][r] * rstd * g0 * sgate[r]);
;         OT[li + 16] = f2bf(o[1][r] * rstd * g1 * sgate[4 + r]);
;       }
;     }
;     __syncthreads();
;     *(u32x4*)(p.O + ((size_t)b * SEQ + n * 16 + (tid >> 4)) * DM + ocol + (tid & 15) * 8) = *(const u32x4*)&OT[(tid >> 4) * 136 + (tid & 15) * 8];
.Lrec_gla_p1w_c:
	ds_write_b128 v151, v[0:3] offset:0
	ds_write_b128 v151, v[4:7] offset:4096
	ds_write_b128 v151, v[8:11] offset:8192
	s_mov_b64 s[26:27], exec
	s_and_b64 exec, exec, s[24:25]
	ds_write_b128 v151, v[12:15] offset:12288
	s_mov_b64 exec, s[26:27]
	s_cmp_gt_u32 s36, 124
	s_cbranch_scc1 .Lrec_gla_p1_nol
	global_load_dwordx4 v[0:3], v152, s[8:9]
	global_load_dwordx4 v[4:7], v153, s[8:9]
	global_load_dwordx4 v[8:11], v154, s[8:9]
	global_load_dwordx4 v[12:15], v172, s[8:9]
	s_add_u32 s8, s8, 0x3100
	s_addc_u32 s9, s9, 0
.Lrec_gla_p1_nol:
	s_add_u32 s36, s36, 1
	s_waitcnt lgkmcnt(0)
	s_cmp_lt_u32 s36, 128
	s_cbranch_scc1 .Lrec_gla_even
	s_barrier
	ds_read_b128 v[224:227], v150 offset:39424
	ds_read_b128 v[228:231], v150 offset:39440
	ds_read_b128 v[204:207], v147 offset:39168
	ds_read_b128 v[208:211], v147 offset:39232
	ds_read_b128 v[212:215], v147 offset:39296
	ds_read_b128 v[216:219], v147 offset:39360
	s_waitcnt vmcnt(0) lgkmcnt(4)
	v_lshlrev_b32_e32 v232, 16, v40
	v_and_b32_e32 v233, 0xffff0000, v40
	v_lshlrev_b32_e32 v234, 16, v41
	v_and_b32_e32 v235, 0xffff0000, v41
	v_lshlrev_b32_e32 v236, 16, v42
	v_and_b32_e32 v237, 0xffff0000, v42
	v_lshlrev_b32_e32 v238, 16, v43
	v_and_b32_e32 v239, 0xffff0000, v43
	v_pk_mul_f32 v[224:225], v[224:225], v[232:233]
	v_pk_mul_f32 v[226:227], v[226:227], v[234:235]
	v_pk_mul_f32 v[228:229], v[228:229], v[236:237]
	v_pk_mul_f32 v[230:231], v[230:231], v[238:239]
	v_cvt_pk_bf16_f32 v232, v224, v225
	v_cvt_pk_bf16_f32 v233, v226, v227
	v_cvt_pk_bf16_f32 v234, v228, v229
	v_cvt_pk_bf16_f32 v235, v230, v231
	s_cmp_lt_u32 s36, 2
	s_cbranch_scc1 .Lrec_gla_dr0
	global_store_dwordx4 v174, v[232:235], s[12:13]
.Lrec_gla_dr0:
	s_add_u32 s12, s12, 0x8000
	s_addc_u32 s13, s13, 0
	s_waitcnt lgkmcnt(0)
	s_waitcnt lgkmcnt(1)
	v_pk_add_f32 v[220:221], v[204:205], v[208:209]
	v_pk_add_f32 v[222:223], v[206:207], v[210:211]
	v_pk_add_f32 v[220:221], v[220:221], v[212:213]
	v_pk_add_f32 v[222:223], v[222:223], v[214:215]
	v_pk_add_f32 v[220:221], v[220:221], v[216:217]
	v_pk_add_f32 v[222:223], v[222:223], v[218:219]
	v_fma_f32 v220, v220, s30, v177
	v_fma_f32 v221, v221, s30, v177
	v_fma_f32 v222, v222, s30, v177
	v_fma_f32 v223, v223, s30, v177
	v_rsq_f32_e32 v220, v220
	v_rsq_f32_e32 v221, v221
	v_rsq_f32_e32 v222, v222
	v_rsq_f32_e32 v223, v223
	s_nop 0
	v_mul_f32_e32 v204, v194, v220
	v_mul_f32_e32 v205, v195, v221
	v_mul_f32_e32 v206, v196, v222
	v_mul_f32_e32 v207, v197, v223
	v_mul_f32_e32 v208, v198, v220
	v_mul_f32_e32 v209, v199, v221
	v_mul_f32_e32 v210, v200, v222
	v_mul_f32_e32 v211, v201, v223
	v_mul_f32_e32 v204, v175, v204
	v_mul_f32_e32 v205, v175, v205
	v_mul_f32_e32 v206, v175, v206
	v_mul_f32_e32 v207, v175, v207
	v_mul_f32_e32 v208, v176, v208
	v_mul_f32_e32 v209, v176, v209
	v_mul_f32_e32 v210, v176, v210
	v_mul_f32_e32 v211, v176, v211
	ds_write_b32 v149, v204 offset:47872
	ds_write_b32 v149, v205 offset:48400
	ds_write_b32 v149, v206 offset:48928
	ds_write_b32 v149, v207 offset:49456
	ds_write_b32 v149, v208 offset:47936
	ds_write_b32 v149, v209 offset:48464
	ds_write_b32 v149, v210 offset:48992
	ds_write_b32 v149, v211 offset:49520
	s_waitcnt lgkmcnt(0)
	s_barrier
	ds_read_b128 v[224:227], v150 offset:47872
	ds_read_b128 v[228:231], v150 offset:47888
	s_waitcnt lgkmcnt(0)
	v_lshlrev_b32_e32 v232, 16, v44
	v_and_b32_e32 v233, 0xffff0000, v44
	v_lshlrev_b32_e32 v234, 16, v45
	v_and_b32_e32 v235, 0xffff0000, v45
	v_lshlrev_b32_e32 v236, 16, v46
	v_and_b32_e32 v237, 0xffff0000, v46
	v_lshlrev_b32_e32 v238, 16, v47
	v_and_b32_e32 v239, 0xffff0000, v47
	v_pk_mul_f32 v[224:225], v[224:225], v[232:233]
	v_pk_mul_f32 v[226:227], v[226:227], v[234:235]
	v_pk_mul_f32 v[228:229], v[228:229], v[236:237]
	v_pk_mul_f32 v[230:231], v[230:231], v[238:239]
	v_cvt_pk_bf16_f32 v232, v224, v225
	v_cvt_pk_bf16_f32 v233, v226, v227
	v_cvt_pk_bf16_f32 v234, v228, v229
	v_cvt_pk_bf16_f32 v235, v230, v231
	s_cmp_lt_u32 s36, 2
	s_cbranch_scc1 .Lrec_gla_dr1
	global_store_dwordx4 v174, v[232:235], s[12:13]
.Lrec_gla_dr1:
	s_branch .LBB0_545

; template <int DK, bool HG, int MODE>
; __device__ void recur_unit(const Params& p, char* smem, int b, int h, char* img, int nstart, int nstep, int nend) {
;     ...
;   const int tid = threadIdx.x, lane = tid & 63, w = tid >> 6, l15 = lane & 15, kg = lane >> 4;
;   const int t = tid & 15, kgp = tid >> 4, k0 = kgp * KPT;
;   const int qcol = HG ? (h * 128) : (2048 + h * 64);
;   const int kcol = HG ? (512 + h * 128) : (2304 + h * 64);
;   const int vcol = HG ? (1024 + h * 128) : (2560 + h * 128);
;   const int gcol = HG ? (1536 + h * 128) : (3088 + h * 128);
;   const int ocol = HG ? (h * 128) : (512 + h * 128);
;   const float* gain = HG ? p.norm_h : p.norm_g;
;   float ba[KPT];
;   if (!HG && MODE == 1) {
;     __syncthreads();
;     for (int i = tid; i < 16 * 64; i += 256) Wa[i] = p.w_a2[(i >> 6) * 256 + h * 64 + (i & 63)];
; #pragma unroll
;     for (int i = 0; i < KPT; i++) ba[i] = p.b_a[h * 64 + k0 + i];
;     __syncthreads();
;   }
;   const float g0 = gain[h * 128 + w * 32 + l15], g1 = gain[h * 128 + w * 32 + 16 + l15];
;   f32x4 S[NKT][2];
; #pragma unroll
;   for (int i = 0; i < NKT; i++) { S[i][0] = f32x4{0, 0, 0, 0}; S[i][1] = f32x4{0, 0, 0, 0}; }
;   float4 pl[4];
;   uint4 pq, pk, pv;
;   u16 psg[8];
;   u32x4 imA[NIM], imB[NIM];
;   u16 psgB[8];
;   auto prefetch = [&](int n, u32x4 (&im)[NIM], u16 (&psg)[8]) {
;     if (MODE == 2) {
;       const char* src = img + (size_t)n * IMG;
; #pragma unroll
;       for (int i = 0; i < NIM; i++) if (tid * 16 + 4096 * i < IMG) im[i] = *(const u32x4*)(src + tid * 16 + 4096 * i);
;       {
;         const u32x4 g = *(const u32x4*)(p.P + ((size_t)b * SEQ + n * 16 + (tid >> 4)) * INC + gcol + (tid & 15) * 8);
;     ...
;   if (MODE == 2) {
;     prefetch(0, imA, psg);
;     prefetch(1, imB, psgB);
;     for (int n = 0; n < SEQ / 16; n += 2) {
;       if (n == 62) mid_barrier(p, smem);
;       step(n, imA, psg); step(n + 1, imB, psgB);
;     }
.Lrec_hg_entry:
	v_readlane_b32 s6, v240, 52
	v_readlane_b32 s2, v240, 24
	v_readlane_b32 s3, v240, 25
	s_nop 3
	s_mul_i32 s26, s6, 0x260000
	s_mul_hi_u32 s27, s6, 0x260000
	s_add_u32 s8, s78, s26
	s_addc_u32 s9, s79, s27
	s_lshr_b32 s26, s6, 2
	s_and_b32 s27, s6, 3
	s_mul_i32 s28, s26, 0xe10000
	s_add_u32 s10, s88, s28
	s_addc_u32 s11, s89, 0
	s_lshl_b32 s28, s27, 8
	s_add_u32 s28, s28, 0xc00
	s_add_u32 s10, s10, s28
	s_addc_u32 s11, s11, 0
	s_lshl_b32 s28, s26, 22
	s_add_u32 s12, s2, s28
	s_addc_u32 s13, s3, 0
	s_lshl_b32 s28, s27, 8
	s_add_u32 s12, s12, s28
	s_addc_u32 s13, s13, 0
	s_sub_u32 s12, s12, 0x10000
	s_subb_u32 s13, s13, 0
	s_mov_b32 s30, 0x3c000000
	s_mov_b32 s4, 0
	s_mov_b32 s36, 0
	v_and_b32_e32 v137, 15, v128
	v_bfe_u32 v139, v128, 4, 2
	v_lshrrev_b32_e32 v142, 6, v128
	v_lshrrev_b32_e32 v178, 4, v128
	v_mul_u32_u24_e32 v202, 272, v137
	v_lshl_add_u32 v144, v139, 3, v202
	v_lshl_add_u32 v202, v142, 5, v137
	v_mul_u32_u24_e32 v202, 40, v202
	v_lshl_add_u32 v145, v139, 3, v202
	v_mul_u32_u24_e32 v202, 40, v137
	v_lshl_add_u32 v146, v139, 3, v202
	v_lshlrev_b32_e32 v147, 4, v139
	v_lshl_add_u32 v148, v142, 6, v147
	v_mul_u32_u24_e32 v202, 0x840, v139
	v_lshl_add_u32 v202, v142, 7, v202
	v_lshl_add_u32 v149, v137, 2, v202
	v_mul_u32_u24_e32 v202, 0x210, v178
	v_lshl_add_u32 v150, v137, 5, v202
	v_lshlrev_b32_e32 v151, 4, v128
	v_add_u32_e32 v152, 0x0, v151
	v_add_u32_e32 v153, 0x1000, v151
	v_add_u32_e32 v154, 0x2000, v151
	v_add_u32_e32 v155, 0x3000, v151
	v_add_u32_e32 v172, 0x4000, v151
	s_movk_i32 s28, 192
	v_cmp_gt_u32_e64 s[24:25], s28, v128
	s_nop 1
	v_cndmask_b32_e64 v172, 0, v172, s[24:25]
	v_mul_u32_u24_e32 v202, 0x1c20, v178
	v_lshl_add_u32 v173, v137, 4, v202
	v_lshlrev_b32_e32 v202, 11, v178
	v_lshl_add_u32 v174, v137, 4, v202
	v_lshl_add_u32 v202, v142, 5, v137
	s_lshl_b32 s28, s27, 7
	v_add_lshl_u32 v202, s28, v202, 2
	global_load_dword v175, v202, s[62:63]
	global_load_dword v176, v202, s[62:63] offset:64
	v_lshlrev_b32_e32 v203, 2, v139
	v_cmp_gt_u32_e64 s[14:15], v203, v137
	v_add_u32_e32 v184, 1, v203
	v_cmp_gt_u32_e64 s[16:17], v184, v137
	v_add_u32_e32 v184, 2, v203
	v_cmp_gt_u32_e64 s[18:19], v184, v137
	v_add_u32_e32 v184, 3, v203
	v_cmp_gt_u32_e64 s[20:21], v184, v137
	v_cmp_eq_u32_e64 s[22:23], 0, v137
	v_mov_b32_e32 v177, 0x3727c5ac
	v_mov_b32_e32 v48, 0
	v_mov_b32_e32 v49, 0
	v_mov_b32_e32 v50, 0
	v_mov_b32_e32 v51, 0
	v_mov_b32_e32 v52, 0
	v_mov_b32_e32 v53, 0
	v_mov_b32_e32 v54, 0
	v_mov_b32_e32 v55, 0
	v_mov_b32_e32 v56, 0
	v_mov_b32_e32 v57, 0
	v_mov_b32_e32 v58, 0
	v_mov_b32_e32 v59, 0
	v_mov_b32_e32 v60, 0
	v_mov_b32_e32 v61, 0
	v_mov_b32_e32 v62, 0
	v_mov_b32_e32 v63, 0
	v_mov_b32_e32 v64, 0
	v_mov_b32_e32 v65, 0
	v_mov_b32_e32 v66, 0
	v_mov_b32_e32 v67, 0
	v_mov_b32_e32 v68, 0
	v_mov_b32_e32 v69, 0
	v_mov_b32_e32 v70, 0
	v_mov_b32_e32 v71, 0
	v_mov_b32_e32 v72, 0
	v_mov_b32_e32 v73, 0
	v_mov_b32_e32 v74, 0
	v_mov_b32_e32 v75, 0
	v_mov_b32_e32 v76, 0
	v_mov_b32_e32 v77, 0
	v_mov_b32_e32 v78, 0
	v_mov_b32_e32 v79, 0
	v_mov_b32_e32 v80, 0
	v_mov_b32_e32 v81, 0
	v_mov_b32_e32 v82, 0
	v_mov_b32_e32 v83, 0
	v_mov_b32_e32 v84, 0
	v_mov_b32_e32 v85, 0
	v_mov_b32_e32 v86, 0
	v_mov_b32_e32 v87, 0
	v_mov_b32_e32 v88, 0
	v_mov_b32_e32 v89, 0
	v_mov_b32_e32 v90, 0
	v_mov_b32_e32 v91, 0
	v_mov_b32_e32 v92, 0
	v_mov_b32_e32 v93, 0
	v_mov_b32_e32 v94, 0
	v_mov_b32_e32 v95, 0
	v_mov_b32_e32 v96, 0
	v_mov_b32_e32 v97, 0
	v_mov_b32_e32 v98, 0
	v_mov_b32_e32 v99, 0
	v_mov_b32_e32 v100, 0
	v_mov_b32_e32 v101, 0
	v_mov_b32_e32 v102, 0
	v_mov_b32_e32 v103, 0
	v_mov_b32_e32 v104, 0
	v_mov_b32_e32 v105, 0
	v_mov_b32_e32 v106, 0
	v_mov_b32_e32 v107, 0
	v_mov_b32_e32 v108, 0
	v_mov_b32_e32 v109, 0
	v_mov_b32_e32 v110, 0
	v_mov_b32_e32 v111, 0
	global_load_dwordx4 v[0:3], v152, s[8:9]
	global_load_dwordx4 v[4:7], v153, s[8:9]
	global_load_dwordx4 v[8:11], v154, s[8:9]
	global_load_dwordx4 v[12:15], v155, s[8:9]
	global_load_dwordx4 v[16:19], v172, s[8:9]
	s_add_u32 s8, s8, 0x4c00
	s_addc_u32 s9, s9, 0
	global_load_dwordx4 v[20:23], v152, s[8:9]
	global_load_dwordx4 v[24:27], v153, s[8:9]
	global_load_dwordx4 v[28:31], v154, s[8:9]
	global_load_dwordx4 v[32:35], v155, s[8:9]
	global_load_dwordx4 v[36:39], v172, s[8:9]
	s_add_u32 s8, s8, 0x4c00
	s_addc_u32 s9, s9, 0
	s_waitcnt vmcnt(5)
	ds_write_b128 v151, v[0:3] offset:0
	ds_write_b128 v151, v[4:7] offset:4096
	ds_write_b128 v151, v[8:11] offset:8192
	ds_write_b128 v151, v[12:15] offset:12288
	s_mov_b64 s[26:27], exec
	s_and_b64 exec, exec, s[24:25]
	ds_write_b128 v151, v[16:19] offset:16384
	s_mov_b64 exec, s[26:27]
	global_load_dwordx4 v[0:3], v152, s[8:9]
	global_load_dwordx4 v[4:7], v153, s[8:9]
	global_load_dwordx4 v[8:11], v154, s[8:9]
	global_load_dwordx4 v[12:15], v155, s[8:9]
	global_load_dwordx4 v[16:19], v172, s[8:9]
	s_add_u32 s8, s8, 0x4c00
	s_addc_u32 s9, s9, 0
	s_waitcnt lgkmcnt(0)
.Lrec_hg_even:
	s_barrier
	ds_read_b128 v[224:227], v150 offset:39424
	ds_read_b128 v[228:231], v150 offset:39440
	ds_read_b64 v[204:205], v144 offset:4352
	ds_read_b64 v[206:207], v144 offset:4384
	ds_read_b64 v[208:209], v144 offset:0
	ds_read_b64 v[210:211], v144 offset:32
	ds_read_b64 v[116:117], v145 offset:13824
	ds_read_b64 v[118:119], v145 offset:14464
	ds_read_b64 v[212:213], v146 offset:8704
	ds_read_b64 v[214:215], v146 offset:9344
	ds_read_b128 v[216:219], v147 offset:18944
	ds_read_b128 v[220:223], v147 offset:19008
	s_sub_u32 s26, s36, 4
	s_cmp_gt_u32 s26, 120
	s_cselect_b32 s29, 1, 0
	v_cvt_pk_bf16_f32 v120, v48, v49
	v_cvt_pk_bf16_f32 v121, v50, v51
	v_cvt_pk_bf16_f32 v122, v56, v57
	v_cvt_pk_bf16_f32 v123, v58, v59
	v_cvt_pk_bf16_f32 v156, v52, v53
	v_cvt_pk_bf16_f32 v157, v54, v55
	v_cvt_pk_bf16_f32 v158, v60, v61
	v_cvt_pk_bf16_f32 v159, v62, v63
	s_waitcnt lgkmcnt(10)
	s_cmp_lg_u32 s29, 0
	s_cbranch_scc1 .Lrec_hg_p0g_d
	s_waitcnt vmcnt(12)
	s_branch .Lrec_hg_p0g_c

; #define STAGE() do { } while (0)
; template <int DK, bool HG, int MODE>
; __device__ void recur_unit(const Params& p, char* smem, int b, int h, char* img, int nstart, int nstep, int nend) {
;     ...
;     f32x4 sc = f32x4{0, 0, 0, 0};
;     bf16x8 qf[NKS];
; #pragma unroll
;     for (int st = 0; st < NKS; st++) {
;       bf16x4 q0 = *(const bf16x4*)&Qt[l15 * LQ + 32 * st + kg * 4];
;       bf16x4 q1 = *(const bf16x4*)&Qt[l15 * LQ + 32 * st + 16 + kg * 4];
;       bf16x4 c0 = *(const bf16x4*)&Kt[l15 * LQ + 32 * st + kg * 4];
;       bf16x4 c1 = *(const bf16x4*)&Kt[l15 * LQ + 32 * st + 16 + kg * 4];
;       qf[st] = bf16x8{q0[0], q0[1], q0[2], q0[3], q1[0], q1[1], q1[2], q1[3]};
;       bf16x8 kf = bf16x8{c0[0], c0[1], c0[2], c0[3], c1[0], c1[1], c1[2], c1[3]};
;       sc = __builtin_amdgcn_mfma_f32_16x16x32_bf16(kf, qf[st], sc, 0, 0, 0);
;     }
;     STAGE();
; #pragma unroll
;     for (int r = 0; r < 4; r++) if (kg * 4 + r > l15) sc[r] = 0.f;
;     bf16x4 pA;
;     {
;       unsigned a = pack2(sc[0], sc[1]), c = pack2(sc[2], sc[3]);
;       pA = bf16x4{(short)(a & 0xffff), (short)(a >> 16), (short)(c & 0xffff), (short)(c >> 16)};
;     }
;     bf16x4 vf[2];
;     f32x4 o[2], oin[2];
;     bf16x8 sbv[2][NKS];
; #pragma unroll
;     for (int vt = 0; vt < 2; vt++) {
;       vf[vt] = *(const bf16x4*)&VT[(w * 32 + vt * 16 + l15) * 20 + kg * 4];
; #pragma unroll
;       for (int st = 0; st < NKS; st++) {
;         unsigned s0 = pack2(S[2 * st][vt][0], S[2 * st][vt][1]), s1 = pack2(S[2 * st][vt][2], S[2 * st][vt][3]);
;         unsigned s2 = pack2(S[2 * st + 1][vt][0], S[2 * st + 1][vt][1]), s3 = pack2(S[2 * st + 1][vt][2], S[2 * st + 1][vt][3]);
;         sbv[vt][st] = bf16x8{(short)(s0 & 0xffff), (short)(s0 >> 16), (short)(s1 & 0xffff), (short)(s1 >> 16),
;                            (short)(s2 & 0xffff), (short)(s2 >> 16), (short)(s3 & 0xffff), (short)(s3 >> 16)};
;       }
;     }
;     STAGE();
; #pragma unroll
;     for (int vt = 0; vt < 2; vt++) {
;       o[vt] = __builtin_amdgcn_mfma_f32_16x16x16bf16_1k(pA, vf[vt], f32x4{0, 0, 0, 0}, 0, 0, 0);
;       oin[vt] = f32x4{0, 0, 0, 0};
; #pragma unroll
;       for (int st = 0; st < NKS; st++) oin[vt] = __builtin_amdgcn_mfma_f32_16x16x32_bf16(qf[st], sbv[vt][st], oin[vt], 0, 0, 0);
;     }
;     STAGE();
;     bf16x4 khf[NKT];
; #pragma unroll
;     for (int kt2 = 0; kt2 < NKT; kt2++) {
.Lrec_hg_p0_nost:
	global_load_dwordx4 v[40:43], v173, s[10:11]
	s_add_u32 s10, s10, 0x1c200
	s_addc_u32 s11, s11, 0
	s_add_u32 s12, s12, 0x8000
	s_addc_u32 s13, s13, 0
	ds_read_b64 v[224:225], v144 offset:4416
	ds_read_b64 v[226:227], v144 offset:4448
	ds_read_b64 v[228:229], v144 offset:64
	ds_read_b64 v[230:231], v144 offset:96
	ds_read_b64 v[232:233], v146 offset:9984
	ds_read_b64 v[234:235], v146 offset:10624
	ds_read_b128 v[236:239], v147 offset:19072
	ds_read_b128 v[112:115], v147 offset:19136
	s_waitcnt lgkmcnt(14)
	v_mfma_f32_16x16x32_bf16 a[0:3], v[204:207], v[208:211], 0
	v_mfma_f32_16x16x32_bf16 a[4:7], v[208:211], v[120:123], 0
	v_mfma_f32_16x16x32_bf16 a[8:11], v[208:211], v[156:159], 0
	s_waitcnt lgkmcnt(8)
	v_pk_mul_f32 v[48:49], v[48:49], v[216:217]
	v_pk_mul_f32 v[50:51], v[50:51], v[218:219]
	v_pk_mul_f32 v[52:53], v[52:53], v[216:217]
	v_pk_mul_f32 v[54:55], v[54:55], v[218:219]
	v_mfma_f32_16x16x16_bf16 v[48:51], v[212:213], v[116:117], v[48:51]
	v_pk_mul_f32 v[56:57], v[56:57], v[220:221]
	v_pk_mul_f32 v[58:59], v[58:59], v[222:223]
	v_mfma_f32_16x16x16_bf16 v[52:55], v[212:213], v[118:119], v[52:55]
	v_pk_mul_f32 v[60:61], v[60:61], v[220:221]
	v_pk_mul_f32 v[62:63], v[62:63], v[222:223]
	v_mfma_f32_16x16x16_bf16 v[56:59], v[214:215], v[116:117], v[56:59]
	v_cvt_pk_bf16_f32 v120, v64, v65
	v_cvt_pk_bf16_f32 v121, v66, v67
	v_mfma_f32_16x16x16_bf16 v[60:63], v[214:215], v[118:119], v[60:63]
	v_cvt_pk_bf16_f32 v122, v72, v73
	v_cvt_pk_bf16_f32 v123, v74, v75
	v_cvt_pk_bf16_f32 v156, v68, v69
	v_cvt_pk_bf16_f32 v157, v70, v71
	v_cvt_pk_bf16_f32 v158, v76, v77
	v_cvt_pk_bf16_f32 v159, v78, v79
	ds_read_b64 v[204:205], v144 offset:4480
	ds_read_b64 v[206:207], v144 offset:4512
	ds_read_b64 v[208:209], v144 offset:128
	ds_read_b64 v[210:211], v144 offset:160
	ds_read_b64 v[212:213], v146 offset:11264
	ds_read_b64 v[214:215], v146 offset:11904
	ds_read_b128 v[216:219], v147 offset:19200
	ds_read_b128 v[220:223], v147 offset:19264
	s_waitcnt lgkmcnt(12)
	v_mfma_f32_16x16x32_bf16 a[0:3], v[224:227], v[228:231], a[0:3]
	v_mfma_f32_16x16x32_bf16 a[4:7], v[228:231], v[120:123], a[4:7]
	v_mfma_f32_16x16x32_bf16 a[8:11], v[228:231], v[156:159], a[8:11]
	s_waitcnt lgkmcnt(8)
	v_pk_mul_f32 v[64:65], v[64:65], v[236:237]
	v_pk_mul_f32 v[66:67], v[66:67], v[238:239]
	v_pk_mul_f32 v[68:69], v[68:69], v[236:237]
	v_pk_mul_f32 v[70:71], v[70:71], v[238:239]
	v_mfma_f32_16x16x16_bf16 v[64:67], v[232:233], v[116:117], v[64:67]
	v_pk_mul_f32 v[72:73], v[72:73], v[112:113]
	v_pk_mul_f32 v[74:75], v[74:75], v[114:115]
	v_mfma_f32_16x16x16_bf16 v[68:71], v[232:233], v[118:119], v[68:71]
	v_pk_mul_f32 v[76:77], v[76:77], v[112:113]
	v_pk_mul_f32 v[78:79], v[78:79], v[114:115]
	v_mfma_f32_16x16x16_bf16 v[72:75], v[234:235], v[116:117], v[72:75]
	v_cvt_pk_bf16_f32 v120, v80, v81
	v_cvt_pk_bf16_f32 v121, v82, v83
	v_mfma_f32_16x16x16_bf16 v[76:79], v[234:235], v[118:119], v[76:79]
	v_cvt_pk_bf16_f32 v122, v88, v89
	v_cvt_pk_bf16_f32 v123, v90, v91
	v_cvt_pk_bf16_f32 v156, v84, v85
	v_cvt_pk_bf16_f32 v157, v86, v87
	v_cvt_pk_bf16_f32 v158, v92, v93
	v_cvt_pk_bf16_f32 v159, v94, v95
	ds_read_b64 v[224:225], v144 offset:4544
	ds_read_b64 v[226:227], v144 offset:4576
	ds_read_b64 v[228:229], v144 offset:192
	ds_read_b64 v[230:231], v144 offset:224
	ds_read_b64 v[232:233], v146 offset:12544
	ds_read_b64 v[234:235], v146 offset:13184
	ds_read_b128 v[236:239], v147 offset:19328
	ds_read_b128 v[112:115], v147 offset:19392
	s_waitcnt lgkmcnt(12)
	v_mfma_f32_16x16x32_bf16 a[0:3], v[204:207], v[208:211], a[0:3]
	v_mfma_f32_16x16x32_bf16 a[4:7], v[208:211], v[120:123], a[4:7]
	v_mfma_f32_16x16x32_bf16 a[8:11], v[208:211], v[156:159], a[8:11]
	s_waitcnt lgkmcnt(8)
	v_pk_mul_f32 v[80:81], v[80:81], v[216:217]
	v_pk_mul_f32 v[82:83], v[82:83], v[218:219]
	v_pk_mul_f32 v[84:85], v[84:85], v[216:217]
	v_pk_mul_f32 v[86:87], v[86:87], v[218:219]
	v_mfma_f32_16x16x16_bf16 v[80:83], v[212:213], v[116:117], v[80:83]
	v_pk_mul_f32 v[88:89], v[88:89], v[220:221]
	v_pk_mul_f32 v[90:91], v[90:91], v[222:223]
	v_mfma_f32_16x16x16_bf16 v[84:87], v[212:213], v[118:119], v[84:87]
	v_pk_mul_f32 v[92:93], v[92:93], v[220:221]
	v_pk_mul_f32 v[94:95], v[94:95], v[222:223]
	v_mfma_f32_16x16x16_bf16 v[88:91], v[214:215], v[116:117], v[88:91]
	v_cvt_pk_bf16_f32 v120, v96, v97
	v_cvt_pk_bf16_f32 v121, v98, v99
	v_mfma_f32_16x16x16_bf16 v[92:95], v[214:215], v[118:119], v[92:95]
	v_cvt_pk_bf16_f32 v122, v104, v105
	v_cvt_pk_bf16_f32 v123, v106, v107
	v_cvt_pk_bf16_f32 v156, v100, v101
	v_cvt_pk_bf16_f32 v157, v102, v103
	v_cvt_pk_bf16_f32 v158, v108, v109
	v_cvt_pk_bf16_f32 v159, v110, v111
	s_waitcnt lgkmcnt(4)
	v_mfma_f32_16x16x32_bf16 a[0:3], v[224:227], v[228:231], a[0:3]
	v_mfma_f32_16x16x32_bf16 a[4:7], v[228:231], v[120:123], a[4:7]
	v_mfma_f32_16x16x32_bf16 a[8:11], v[228:231], v[156:159], a[8:11]
	s_waitcnt lgkmcnt(0)
; __device__ __forceinline__ float bf2f(u16 v) { return __uint_as_float(((unsigned)v) << 16); }
; #define STAGE() do { } while (0)
; template <int DK, bool HG, int MODE>
; __device__ void recur_unit(const Params& p, char* smem, int b, int h, char* img, int nstart, int nstep, int nend) {
;     ...
; #pragma unroll
;     for (int vt = 0; vt < 2; vt++) {
;       o[vt] = __builtin_amdgcn_mfma_f32_16x16x16bf16_1k(pA, vf[vt], f32x4{0, 0, 0, 0}, 0, 0, 0);
;       oin[vt] = f32x4{0, 0, 0, 0};
; #pragma unroll
;       for (int st = 0; st < NKS; st++) oin[vt] = __builtin_amdgcn_mfma_f32_16x16x32_bf16(qf[st], sbv[vt][st], oin[vt], 0, 0, 0);
;     }
;     STAGE();
;     bf16x4 khf[NKT];
; #pragma unroll
;     for (int kt2 = 0; kt2 < NKT; kt2++) {
;       khf[kt2] = *(const bf16x4*)&KhT[(16 * kt2 + l15) * 20 + kg * 4];
;       float4 g4 = *(const float4*)&Gch[16 * kt2 + kg * 4];
;       f32x4 gv = f32x4{g4.x, g4.y, g4.z, g4.w};
;       S[kt2][0] *= gv; S[kt2][1] *= gv;
;     }
;     STAGE();
; #pragma unroll
;     for (int kt2 = 0; kt2 < NKT; kt2++) {
; #pragma unroll
;       for (int vt = 0; vt < 2; vt++)
;         S[kt2][vt] = __builtin_amdgcn_mfma_f32_16x16x16bf16_1k(khf[kt2], vf[vt], S[kt2][vt], 0, 0, 0);
;     }
;     STAGE();
;     float ss[4];
; #pragma unroll
;     for (int r = 0; r < 4; r++) {
;       o[0][r] += oin[0][r]; o[1][r] += oin[1][r];
;       float s = o[0][r] * o[0][r] + o[1][r] * o[1][r];
;       s = dpp_row_sum(s);
;       ss[r] = s;
;     }
;     if (l15 == 0) *(float4*)&SS[w * 16 + kg * 4] = make_float4(ss[0], ss[1], ss[2], ss[3]);
;     __syncthreads();
;     {
;       float4 a0 = *(const float4*)&SS[0 * 16 + kg * 4], a1 = *(const float4*)&SS[1 * 16 + kg * 4];
;       float4 a2 = *(const float4*)&SS[2 * 16 + kg * 4], a3 = *(const float4*)&SS[3 * 16 + kg * 4];
;       float tot[4] = {a0.x + a1.x + a2.x + a3.x, a0.y + a1.y + a2.y + a3.y, a0.z + a1.z + a2.z + a3.z, a0.w + a1.w + a2.w + a3.w};
; #pragma unroll
;       for (int r = 0; r < 4; r++) {
;         const float rstd = rsqrtf(tot[r] * (1.f / 128.f) + LN_EPS);
;         const int li = (kg * 4 + r) * 136 + w * 32 + l15;
;         sgate[r] = bf2f(GT[li]); sgate[4 + r] = bf2f(GT[li + 16]);
;         OT[li] = f2bf(o[0][r] * rstd * g0 * sgate[r]);
;         OT[li + 16] = f2bf(o[1][r] * rstd * g1 * sgate[4 + r]);
;       }
	v_pk_mul_f32 v[96:97], v[96:97], v[236:237]
	v_pk_mul_f32 v[98:99], v[98:99], v[238:239]
	v_pk_mul_f32 v[100:101], v[100:101], v[236:237]
	v_pk_mul_f32 v[102:103], v[102:103], v[238:239]
	v_mfma_f32_16x16x16_bf16 v[96:99], v[232:233], v[116:117], v[96:99]
	v_pk_mul_f32 v[104:105], v[104:105], v[112:113]
	v_pk_mul_f32 v[106:107], v[106:107], v[114:115]
	v_mfma_f32_16x16x16_bf16 v[100:103], v[232:233], v[118:119], v[100:103]
	v_pk_mul_f32 v[108:109], v[108:109], v[112:113]
	v_pk_mul_f32 v[110:111], v[110:111], v[114:115]
	v_mfma_f32_16x16x16_bf16 v[104:107], v[234:235], v[116:117], v[104:107]
	s_nop 1
	v_mfma_f32_16x16x16_bf16 v[108:111], v[234:235], v[118:119], v[108:111]
	ds_read_b128 v[204:207], v147 offset:39168
	ds_read_b128 v[208:211], v147 offset:39232
	ds_read_b128 v[212:215], v147 offset:39296
	ds_read_b128 v[216:219], v147 offset:39360
	v_accvgpr_read_b32 v224, a0
	v_accvgpr_read_b32 v225, a1
	v_accvgpr_read_b32 v226, a2
	v_accvgpr_read_b32 v227, a3
	v_accvgpr_read_b32 v228, a4
	v_accvgpr_read_b32 v229, a5
	v_accvgpr_read_b32 v230, a6
	v_accvgpr_read_b32 v231, a7
	v_accvgpr_read_b32 v232, a8
	v_accvgpr_read_b32 v233, a9
	v_accvgpr_read_b32 v234, a10
	v_accvgpr_read_b32 v235, a11
	v_cndmask_b32_e64 v224, v224, 0, s[14:15]
	v_cndmask_b32_e64 v225, v225, 0, s[16:17]
	v_cndmask_b32_e64 v226, v226, 0, s[18:19]
	v_cndmask_b32_e64 v227, v227, 0, s[20:21]
	v_cvt_pk_bf16_f32 v140, v224, v225
	v_cvt_pk_bf16_f32 v141, v226, v227
	s_nop 1
	v_mfma_f32_16x16x16_bf16 v[186:189], v[140:141], v[116:117], 0
	v_mfma_f32_16x16x16_bf16 v[190:193], v[140:141], v[118:119], 0
	s_nop 7
	s_nop 1
	v_pk_add_f32 v[186:187], v[186:187], v[228:229]
	v_pk_add_f32 v[188:189], v[188:189], v[230:231]
	v_pk_add_f32 v[190:191], v[190:191], v[232:233]
	v_pk_add_f32 v[192:193], v[192:193], v[234:235]
	v_pk_mul_f32 v[236:237], v[190:191], v[190:191]
	v_pk_mul_f32 v[238:239], v[192:193], v[192:193]
	v_pk_fma_f32 v[112:113], v[186:187], v[186:187], v[236:237]
	v_pk_fma_f32 v[114:115], v[188:189], v[188:189], v[238:239]
	s_nop 1
	v_add_f32_dpp v112, v112, v112 row_ror:8 row_mask:0xf bank_mask:0xf
	v_add_f32_dpp v113, v113, v113 row_ror:8 row_mask:0xf bank_mask:0xf
	v_add_f32_dpp v114, v114, v114 row_ror:8 row_mask:0xf bank_mask:0xf
	v_add_f32_dpp v115, v115, v115 row_ror:8 row_mask:0xf bank_mask:0xf
	v_add_f32_dpp v112, v112, v112 row_ror:4 row_mask:0xf bank_mask:0xf
	v_add_f32_dpp v113, v113, v113 row_ror:4 row_mask:0xf bank_mask:0xf
	v_add_f32_dpp v114, v114, v114 row_ror:4 row_mask:0xf bank_mask:0xf
	v_add_f32_dpp v115, v115, v115 row_ror:4 row_mask:0xf bank_mask:0xf
	v_add_f32_dpp v112, v112, v112 row_ror:2 row_mask:0xf bank_mask:0xf
	v_add_f32_dpp v113, v113, v113 row_ror:2 row_mask:0xf bank_mask:0xf
	v_add_f32_dpp v114, v114, v114 row_ror:2 row_mask:0xf bank_mask:0xf
	v_add_f32_dpp v115, v115, v115 row_ror:2 row_mask:0xf bank_mask:0xf
	v_add_f32_dpp v112, v112, v112 row_ror:1 row_mask:0xf bank_mask:0xf
	v_add_f32_dpp v113, v113, v113 row_ror:1 row_mask:0xf bank_mask:0xf
	v_add_f32_dpp v114, v114, v114 row_ror:1 row_mask:0xf bank_mask:0xf
	v_add_f32_dpp v115, v115, v115 row_ror:1 row_mask:0xf bank_mask:0xf
	s_mov_b64 s[26:27], exec
	s_and_b64 exec, exec, s[22:23]
	ds_write_b128 v148, v[112:115] offset:38912
	s_mov_b64 exec, s[26:27]
	s_waitcnt lgkmcnt(1)
	v_pk_add_f32 v[220:221], v[204:205], v[208:209]
	v_pk_add_f32 v[222:223], v[206:207], v[210:211]
	v_pk_add_f32 v[220:221], v[220:221], v[212:213]
	v_pk_add_f32 v[222:223], v[222:223], v[214:215]
	v_pk_add_f32 v[220:221], v[220:221], v[216:217]
	v_pk_add_f32 v[222:223], v[222:223], v[218:219]
	v_fma_f32 v220, v220, s30, v177
	v_fma_f32 v221, v221, s30, v177
	v_fma_f32 v222, v222, s30, v177
	v_fma_f32 v223, v223, s30, v177
	v_rsq_f32_e32 v220, v220
	v_rsq_f32_e32 v221, v221
	v_rsq_f32_e32 v222, v222
	v_rsq_f32_e32 v223, v223
	s_nop 0
	v_mul_f32_e32 v204, v194, v220
	v_mul_f32_e32 v205, v195, v221
	v_mul_f32_e32 v206, v196, v222
	v_mul_f32_e32 v207, v197, v223
	v_mul_f32_e32 v208, v198, v220
	v_mul_f32_e32 v209, v199, v221
	v_mul_f32_e32 v210, v200, v222
	v_mul_f32_e32 v211, v201, v223
	v_mul_f32_e32 v204, v175, v204
	v_mul_f32_e32 v205, v175, v205
	v_mul_f32_e32 v206, v175, v206
	v_mul_f32_e32 v207, v175, v207
	v_mul_f32_e32 v208, v176, v208
	v_mul_f32_e32 v209, v176, v209
	v_mul_f32_e32 v210, v176, v210
	v_mul_f32_e32 v211, v176, v211
	ds_write_b32 v149, v204 offset:47872
	ds_write_b32 v149, v205 offset:48400
	ds_write_b32 v149, v206 offset:48928
	ds_write_b32 v149, v207 offset:49456
	ds_write_b32 v149, v208 offset:47936
	ds_write_b32 v149, v209 offset:48464
	ds_write_b32 v149, v210 offset:48992
	ds_write_b32 v149, v211 offset:49520
	s_cmp_lg_u32 s29, 0
	s_cbranch_scc1 .Lrec_hg_p0w_d
	s_waitcnt vmcnt(9)
	s_branch .Lrec_hg_p0w_c

; template <int DK, bool HG, int MODE>
; __device__ void recur_unit(const Params& p, char* smem, int b, int h, char* img, int nstart, int nstep, int nend) {
;     ...
;   auto step = [&](int n, u32x4 (&im)[NIM], u16 (&psg)[8]) {
;     float sgate[8];
;     if (MODE == 2) {
; #pragma unroll
;       for (int i = 0; i < NIM; i++) if (tid * 16 + 4096 * i < IMG) *(u32x4*)(smem + tid * 16 + 4096 * i) = im[i];
;       {
;         u32x4 g;
;         g[0] = (unsigned)psg[0] | ((unsigned)psg[1] << 16); g[1] = (unsigned)psg[2] | ((unsigned)psg[3] << 16);
;         g[2] = (unsigned)psg[4] | ((unsigned)psg[5] << 16); g[3] = (unsigned)psg[6] | ((unsigned)psg[7] << 16);
;         *(u32x4*)&GT[(tid >> 4) * 136 + (tid & 15) * 8] = g;
;       }
;       __builtin_amdgcn_sched_barrier(0);
;       if (n + PFD * nstep < nend) prefetch(n + PFD * nstep, im, psg);
;       __builtin_amdgcn_sched_barrier(0);
.Lrec_hg_p0w_c:
	ds_write_b128 v151, v[20:23] offset:19456
	ds_write_b128 v151, v[24:27] offset:23552
	ds_write_b128 v151, v[28:31] offset:27648
	ds_write_b128 v151, v[32:35] offset:31744
	s_mov_b64 s[26:27], exec
	s_and_b64 exec, exec, s[24:25]
	ds_write_b128 v151, v[36:39] offset:35840
	s_mov_b64 exec, s[26:27]
	s_cmp_gt_u32 s36, 124
	s_cbranch_scc1 .Lrec_hg_p0_nol
	global_load_dwordx4 v[20:23], v152, s[8:9]
	global_load_dwordx4 v[24:27], v153, s[8:9]
	global_load_dwordx4 v[28:31], v154, s[8:9]
	global_load_dwordx4 v[32:35], v155, s[8:9]
	global_load_dwordx4 v[36:39], v172, s[8:9]
	s_add_u32 s8, s8, 0x4c00
	s_addc_u32 s9, s9, 0

; template <int DK, bool HG, int MODE>
; __device__ void recur_unit(const Params& p, char* smem, int b, int h, char* img, int nstart, int nstep, int nend) {
;     ...
;     f32x4 sc = f32x4{0, 0, 0, 0};
;     bf16x8 qf[NKS];
; #pragma unroll
;     for (int st = 0; st < NKS; st++) {
;       bf16x4 q0 = *(const bf16x4*)&Qt[l15 * LQ + 32 * st + kg * 4];
;       bf16x4 q1 = *(const bf16x4*)&Qt[l15 * LQ + 32 * st + 16 + kg * 4];
;       bf16x4 c0 = *(const bf16x4*)&Kt[l15 * LQ + 32 * st + kg * 4];
;       bf16x4 c1 = *(const bf16x4*)&Kt[l15 * LQ + 32 * st + 16 + kg * 4];
;       qf[st] = bf16x8{q0[0], q0[1], q0[2], q0[3], q1[0], q1[1], q1[2], q1[3]};
;       bf16x8 kf = bf16x8{c0[0], c0[1], c0[2], c0[3], c1[0], c1[1], c1[2], c1[3]};
;       sc = __builtin_amdgcn_mfma_f32_16x16x32_bf16(kf, qf[st], sc, 0, 0, 0);
.Lrec_hg_midret:
	ds_read_b128 v[224:227], v150 offset:47872
	ds_read_b128 v[228:231], v150 offset:47888
	ds_read_b64 v[204:205], v144 offset:23808
	ds_read_b64 v[206:207], v144 offset:23840
	ds_read_b64 v[208:209], v144 offset:19456
	ds_read_b64 v[210:211], v144 offset:19488
	ds_read_b64 v[116:117], v145 offset:33280
	ds_read_b64 v[118:119], v145 offset:33920
	ds_read_b64 v[212:213], v146 offset:28160
	ds_read_b64 v[214:215], v146 offset:28800
	ds_read_b128 v[216:219], v147 offset:38400
	ds_read_b128 v[220:223], v147 offset:38464
	s_sub_u32 s26, s36, 4
	s_cmp_gt_u32 s26, 120
	s_cselect_b32 s29, 1, 0
	v_cvt_pk_bf16_f32 v120, v48, v49
	v_cvt_pk_bf16_f32 v121, v50, v51
	v_cvt_pk_bf16_f32 v122, v56, v57
	v_cvt_pk_bf16_f32 v123, v58, v59
	v_cvt_pk_bf16_f32 v156, v52, v53
	v_cvt_pk_bf16_f32 v157, v54, v55
	v_cvt_pk_bf16_f32 v158, v60, v61
	v_cvt_pk_bf16_f32 v159, v62, v63
	s_waitcnt lgkmcnt(10)
	s_cmp_lg_u32 s29, 0
	s_cbranch_scc1 .Lrec_hg_p1g_d
	s_waitcnt vmcnt(12)
	s_branch .Lrec_hg_p1g_c

; #define STAGE() do { } while (0)
; template <int DK, bool HG, int MODE>
; __device__ void recur_unit(const Params& p, char* smem, int b, int h, char* img, int nstart, int nstep, int nend) {
;     ...
;     f32x4 sc = f32x4{0, 0, 0, 0};
;     bf16x8 qf[NKS];
; #pragma unroll
;     for (int st = 0; st < NKS; st++) {
;       bf16x4 q0 = *(const bf16x4*)&Qt[l15 * LQ + 32 * st + kg * 4];
;       bf16x4 q1 = *(const bf16x4*)&Qt[l15 * LQ + 32 * st + 16 + kg * 4];
;       bf16x4 c0 = *(const bf16x4*)&Kt[l15 * LQ + 32 * st + kg * 4];
;       bf16x4 c1 = *(const bf16x4*)&Kt[l15 * LQ + 32 * st + 16 + kg * 4];
;       qf[st] = bf16x8{q0[0], q0[1], q0[2], q0[3], q1[0], q1[1], q1[2], q1[3]};
;       bf16x8 kf = bf16x8{c0[0], c0[1], c0[2], c0[3], c1[0], c1[1], c1[2], c1[3]};
;       sc = __builtin_amdgcn_mfma_f32_16x16x32_bf16(kf, qf[st], sc, 0, 0, 0);
;     }
;     STAGE();
; #pragma unroll
;     for (int r = 0; r < 4; r++) if (kg * 4 + r > l15) sc[r] = 0.f;
;     bf16x4 pA;
;     {
;       unsigned a = pack2(sc[0], sc[1]), c = pack2(sc[2], sc[3]);
;       pA = bf16x4{(short)(a & 0xffff), (short)(a >> 16), (short)(c & 0xffff), (short)(c >> 16)};
;     }
;     bf16x4 vf[2];
;     f32x4 o[2], oin[2];
;     bf16x8 sbv[2][NKS];
; #pragma unroll
;     for (int vt = 0; vt < 2; vt++) {
;       vf[vt] = *(const bf16x4*)&VT[(w * 32 + vt * 16 + l15) * 20 + kg * 4];
; #pragma unroll
;       for (int st = 0; st < NKS; st++) {
;         unsigned s0 = pack2(S[2 * st][vt][0], S[2 * st][vt][1]), s1 = pack2(S[2 * st][vt][2], S[2 * st][vt][3]);
;         unsigned s2 = pack2(S[2 * st + 1][vt][0], S[2 * st + 1][vt][1]), s3 = pack2(S[2 * st + 1][vt][2], S[2 * st + 1][vt][3]);
;         sbv[vt][st] = bf16x8{(short)(s0 & 0xffff), (short)(s0 >> 16), (short)(s1 & 0xffff), (short)(s1 >> 16),
;                            (short)(s2 & 0xffff), (short)(s2 >> 16), (short)(s3 & 0xffff), (short)(s3 >> 16)};
;       }
;     }
;     STAGE();
; #pragma unroll
;     for (int vt = 0; vt < 2; vt++) {
;       o[vt] = __builtin_amdgcn_mfma_f32_16x16x16bf16_1k(pA, vf[vt], f32x4{0, 0, 0, 0}, 0, 0, 0);
;       oin[vt] = f32x4{0, 0, 0, 0};
; #pragma unroll
;       for (int st = 0; st < NKS; st++) oin[vt] = __builtin_amdgcn_mfma_f32_16x16x32_bf16(qf[st], sbv[vt][st], oin[vt], 0, 0, 0);
;     }
;     STAGE();
;     bf16x4 khf[NKT];
; #pragma unroll
;     for (int kt2 = 0; kt2 < NKT; kt2++) {
.Lrec_hg_p1_nost:
	global_load_dwordx4 v[44:47], v173, s[10:11]
	s_add_u32 s10, s10, 0x1c200
	s_addc_u32 s11, s11, 0
	s_add_u32 s12, s12, 0x8000
	s_addc_u32 s13, s13, 0
	ds_read_b64 v[224:225], v144 offset:23872
	ds_read_b64 v[226:227], v144 offset:23904
	ds_read_b64 v[228:229], v144 offset:19520
	ds_read_b64 v[230:231], v144 offset:19552
	ds_read_b64 v[232:233], v146 offset:29440
	ds_read_b64 v[234:235], v146 offset:30080
	ds_read_b128 v[236:239], v147 offset:38528
	ds_read_b128 v[112:115], v147 offset:38592
	s_waitcnt lgkmcnt(14)
	v_mfma_f32_16x16x32_bf16 a[0:3], v[204:207], v[208:211], 0
	v_mfma_f32_16x16x32_bf16 a[4:7], v[208:211], v[120:123], 0
	v_mfma_f32_16x16x32_bf16 a[8:11], v[208:211], v[156:159], 0
	s_waitcnt lgkmcnt(8)
	v_pk_mul_f32 v[48:49], v[48:49], v[216:217]
	v_pk_mul_f32 v[50:51], v[50:51], v[218:219]
	v_pk_mul_f32 v[52:53], v[52:53], v[216:217]
	v_pk_mul_f32 v[54:55], v[54:55], v[218:219]
	v_mfma_f32_16x16x16_bf16 v[48:51], v[212:213], v[116:117], v[48:51]
	v_pk_mul_f32 v[56:57], v[56:57], v[220:221]
	v_pk_mul_f32 v[58:59], v[58:59], v[222:223]
	v_mfma_f32_16x16x16_bf16 v[52:55], v[212:213], v[118:119], v[52:55]
	v_pk_mul_f32 v[60:61], v[60:61], v[220:221]
	v_pk_mul_f32 v[62:63], v[62:63], v[222:223]
	v_mfma_f32_16x16x16_bf16 v[56:59], v[214:215], v[116:117], v[56:59]
	v_cvt_pk_bf16_f32 v120, v64, v65
	v_cvt_pk_bf16_f32 v121, v66, v67
	v_mfma_f32_16x16x16_bf16 v[60:63], v[214:215], v[118:119], v[60:63]
	v_cvt_pk_bf16_f32 v122, v72, v73
	v_cvt_pk_bf16_f32 v123, v74, v75
	v_cvt_pk_bf16_f32 v156, v68, v69
	v_cvt_pk_bf16_f32 v157, v70, v71
	v_cvt_pk_bf16_f32 v158, v76, v77
	v_cvt_pk_bf16_f32 v159, v78, v79
	ds_read_b64 v[204:205], v144 offset:23936
	ds_read_b64 v[206:207], v144 offset:23968
	ds_read_b64 v[208:209], v144 offset:19584
	ds_read_b64 v[210:211], v144 offset:19616
	ds_read_b64 v[212:213], v146 offset:30720
	ds_read_b64 v[214:215], v146 offset:31360
	ds_read_b128 v[216:219], v147 offset:38656
	ds_read_b128 v[220:223], v147 offset:38720
	s_waitcnt lgkmcnt(12)
	v_mfma_f32_16x16x32_bf16 a[0:3], v[224:227], v[228:231], a[0:3]
	v_mfma_f32_16x16x32_bf16 a[4:7], v[228:231], v[120:123], a[4:7]
	v_mfma_f32_16x16x32_bf16 a[8:11], v[228:231], v[156:159], a[8:11]
	s_waitcnt lgkmcnt(8)
	v_pk_mul_f32 v[64:65], v[64:65], v[236:237]
	v_pk_mul_f32 v[66:67], v[66:67], v[238:239]
	v_pk_mul_f32 v[68:69], v[68:69], v[236:237]
	v_pk_mul_f32 v[70:71], v[70:71], v[238:239]
	v_mfma_f32_16x16x16_bf16 v[64:67], v[232:233], v[116:117], v[64:67]
	v_pk_mul_f32 v[72:73], v[72:73], v[112:113]
	v_pk_mul_f32 v[74:75], v[74:75], v[114:115]
	v_mfma_f32_16x16x16_bf16 v[68:71], v[232:233], v[118:119], v[68:71]
	v_pk_mul_f32 v[76:77], v[76:77], v[112:113]
	v_pk_mul_f32 v[78:79], v[78:79], v[114:115]
	v_mfma_f32_16x16x16_bf16 v[72:75], v[234:235], v[116:117], v[72:75]
	v_cvt_pk_bf16_f32 v120, v80, v81
	v_cvt_pk_bf16_f32 v121, v82, v83
	v_mfma_f32_16x16x16_bf16 v[76:79], v[234:235], v[118:119], v[76:79]
	v_cvt_pk_bf16_f32 v122, v88, v89
	v_cvt_pk_bf16_f32 v123, v90, v91
	v_cvt_pk_bf16_f32 v156, v84, v85
	v_cvt_pk_bf16_f32 v157, v86, v87
	v_cvt_pk_bf16_f32 v158, v92, v93
	v_cvt_pk_bf16_f32 v159, v94, v95
	ds_read_b64 v[224:225], v144 offset:24000
	ds_read_b64 v[226:227], v144 offset:24032
	ds_read_b64 v[228:229], v144 offset:19648
	ds_read_b64 v[230:231], v144 offset:19680
	ds_read_b64 v[232:233], v146 offset:32000
	ds_read_b64 v[234:235], v146 offset:32640
	ds_read_b128 v[236:239], v147 offset:38784
	ds_read_b128 v[112:115], v147 offset:38848
	s_waitcnt lgkmcnt(12)
	v_mfma_f32_16x16x32_bf16 a[0:3], v[204:207], v[208:211], a[0:3]
	v_mfma_f32_16x16x32_bf16 a[4:7], v[208:211], v[120:123], a[4:7]
	v_mfma_f32_16x16x32_bf16 a[8:11], v[208:211], v[156:159], a[8:11]
	s_waitcnt lgkmcnt(8)
	v_pk_mul_f32 v[80:81], v[80:81], v[216:217]
	v_pk_mul_f32 v[82:83], v[82:83], v[218:219]
	v_pk_mul_f32 v[84:85], v[84:85], v[216:217]
	v_pk_mul_f32 v[86:87], v[86:87], v[218:219]
	v_mfma_f32_16x16x16_bf16 v[80:83], v[212:213], v[116:117], v[80:83]
	v_pk_mul_f32 v[88:89], v[88:89], v[220:221]
	v_pk_mul_f32 v[90:91], v[90:91], v[222:223]
	v_mfma_f32_16x16x16_bf16 v[84:87], v[212:213], v[118:119], v[84:87]
	v_pk_mul_f32 v[92:93], v[92:93], v[220:221]
	v_pk_mul_f32 v[94:95], v[94:95], v[222:223]
	v_mfma_f32_16x16x16_bf16 v[88:91], v[214:215], v[116:117], v[88:91]
	v_cvt_pk_bf16_f32 v120, v96, v97
	v_cvt_pk_bf16_f32 v121, v98, v99
	v_mfma_f32_16x16x16_bf16 v[92:95], v[214:215], v[118:119], v[92:95]
	v_cvt_pk_bf16_f32 v122, v104, v105
	v_cvt_pk_bf16_f32 v123, v106, v107
	v_cvt_pk_bf16_f32 v156, v100, v101
	v_cvt_pk_bf16_f32 v157, v102, v103
	v_cvt_pk_bf16_f32 v158, v108, v109
	v_cvt_pk_bf16_f32 v159, v110, v111
	s_waitcnt lgkmcnt(4)
	v_mfma_f32_16x16x32_bf16 a[0:3], v[224:227], v[228:231], a[0:3]
	v_mfma_f32_16x16x32_bf16 a[4:7], v[228:231], v[120:123], a[4:7]
	v_mfma_f32_16x16x32_bf16 a[8:11], v[228:231], v[156:159], a[8:11]
	s_waitcnt lgkmcnt(0)
; __device__ __forceinline__ float bf2f(u16 v) { return __uint_as_float(((unsigned)v) << 16); }
; #define STAGE() do { } while (0)
; template <int DK, bool HG, int MODE>
; __device__ void recur_unit(const Params& p, char* smem, int b, int h, char* img, int nstart, int nstep, int nend) {
;     ...
; #pragma unroll
;     for (int vt = 0; vt < 2; vt++) {
;       o[vt] = __builtin_amdgcn_mfma_f32_16x16x16bf16_1k(pA, vf[vt], f32x4{0, 0, 0, 0}, 0, 0, 0);
;       oin[vt] = f32x4{0, 0, 0, 0};
; #pragma unroll
;       for (int st = 0; st < NKS; st++) oin[vt] = __builtin_amdgcn_mfma_f32_16x16x32_bf16(qf[st], sbv[vt][st], oin[vt], 0, 0, 0);
;     }
;     STAGE();
;     bf16x4 khf[NKT];
; #pragma unroll
;     for (int kt2 = 0; kt2 < NKT; kt2++) {
;       khf[kt2] = *(const bf16x4*)&KhT[(16 * kt2 + l15) * 20 + kg * 4];
;       float4 g4 = *(const float4*)&Gch[16 * kt2 + kg * 4];
;       f32x4 gv = f32x4{g4.x, g4.y, g4.z, g4.w};
;       S[kt2][0] *= gv; S[kt2][1] *= gv;
;     }
;     STAGE();
; #pragma unroll
;     for (int kt2 = 0; kt2 < NKT; kt2++) {
; #pragma unroll
;       for (int vt = 0; vt < 2; vt++)
;         S[kt2][vt] = __builtin_amdgcn_mfma_f32_16x16x16bf16_1k(khf[kt2], vf[vt], S[kt2][vt], 0, 0, 0);
;     }
;     STAGE();
;     float ss[4];
; #pragma unroll
;     for (int r = 0; r < 4; r++) {
;       o[0][r] += oin[0][r]; o[1][r] += oin[1][r];
;       float s = o[0][r] * o[0][r] + o[1][r] * o[1][r];
;       s = dpp_row_sum(s);
;       ss[r] = s;
;     }
;     if (l15 == 0) *(float4*)&SS[w * 16 + kg * 4] = make_float4(ss[0], ss[1], ss[2], ss[3]);
;     __syncthreads();
;     {
;       float4 a0 = *(const float4*)&SS[0 * 16 + kg * 4], a1 = *(const float4*)&SS[1 * 16 + kg * 4];
;       float4 a2 = *(const float4*)&SS[2 * 16 + kg * 4], a3 = *(const float4*)&SS[3 * 16 + kg * 4];
;       float tot[4] = {a0.x + a1.x + a2.x + a3.x, a0.y + a1.y + a2.y + a3.y, a0.z + a1.z + a2.z + a3.z, a0.w + a1.w + a2.w + a3.w};
; #pragma unroll
;       for (int r = 0; r < 4; r++) {
;         const float rstd = rsqrtf(tot[r] * (1.f / 128.f) + LN_EPS);
;         const int li = (kg * 4 + r) * 136 + w * 32 + l15;
;         sgate[r] = bf2f(GT[li]); sgate[4 + r] = bf2f(GT[li + 16]);
;         OT[li] = f2bf(o[0][r] * rstd * g0 * sgate[r]);
;         OT[li + 16] = f2bf(o[1][r] * rstd * g1 * sgate[4 + r]);
;       }
	v_pk_mul_f32 v[96:97], v[96:97], v[236:237]
	v_pk_mul_f32 v[98:99], v[98:99], v[238:239]
	v_pk_mul_f32 v[100:101], v[100:101], v[236:237]
	v_pk_mul_f32 v[102:103], v[102:103], v[238:239]
	v_mfma_f32_16x16x16_bf16 v[96:99], v[232:233], v[116:117], v[96:99]
	v_pk_mul_f32 v[104:105], v[104:105], v[112:113]
	v_pk_mul_f32 v[106:107], v[106:107], v[114:115]
	v_mfma_f32_16x16x16_bf16 v[100:103], v[232:233], v[118:119], v[100:103]
	v_pk_mul_f32 v[108:109], v[108:109], v[112:113]
	v_pk_mul_f32 v[110:111], v[110:111], v[114:115]
	v_mfma_f32_16x16x16_bf16 v[104:107], v[234:235], v[116:117], v[104:107]
	s_nop 1
	v_mfma_f32_16x16x16_bf16 v[108:111], v[234:235], v[118:119], v[108:111]
	ds_read_b128 v[204:207], v147 offset:38912
	ds_read_b128 v[208:211], v147 offset:38976
	ds_read_b128 v[212:215], v147 offset:39040
	ds_read_b128 v[216:219], v147 offset:39104
	v_accvgpr_read_b32 v224, a0
	v_accvgpr_read_b32 v225, a1
	v_accvgpr_read_b32 v226, a2
	v_accvgpr_read_b32 v227, a3
	v_accvgpr_read_b32 v228, a4
	v_accvgpr_read_b32 v229, a5
	v_accvgpr_read_b32 v230, a6
	v_accvgpr_read_b32 v231, a7
	v_accvgpr_read_b32 v232, a8
	v_accvgpr_read_b32 v233, a9
	v_accvgpr_read_b32 v234, a10
	v_accvgpr_read_b32 v235, a11
	v_cndmask_b32_e64 v224, v224, 0, s[14:15]
	v_cndmask_b32_e64 v225, v225, 0, s[16:17]
	v_cndmask_b32_e64 v226, v226, 0, s[18:19]
	v_cndmask_b32_e64 v227, v227, 0, s[20:21]
	v_cvt_pk_bf16_f32 v140, v224, v225
	v_cvt_pk_bf16_f32 v141, v226, v227
	s_nop 1
	v_mfma_f32_16x16x16_bf16 v[194:197], v[140:141], v[116:117], 0
	v_mfma_f32_16x16x16_bf16 v[198:201], v[140:141], v[118:119], 0
	s_nop 7
	s_nop 1
	v_pk_add_f32 v[194:195], v[194:195], v[228:229]
	v_pk_add_f32 v[196:197], v[196:197], v[230:231]
	v_pk_add_f32 v[198:199], v[198:199], v[232:233]
	v_pk_add_f32 v[200:201], v[200:201], v[234:235]
	v_pk_mul_f32 v[236:237], v[198:199], v[198:199]
	v_pk_mul_f32 v[238:239], v[200:201], v[200:201]
	v_pk_fma_f32 v[112:113], v[194:195], v[194:195], v[236:237]
	v_pk_fma_f32 v[114:115], v[196:197], v[196:197], v[238:239]
	s_nop 1
	v_add_f32_dpp v112, v112, v112 row_ror:8 row_mask:0xf bank_mask:0xf
	v_add_f32_dpp v113, v113, v113 row_ror:8 row_mask:0xf bank_mask:0xf
	v_add_f32_dpp v114, v114, v114 row_ror:8 row_mask:0xf bank_mask:0xf
	v_add_f32_dpp v115, v115, v115 row_ror:8 row_mask:0xf bank_mask:0xf
	v_add_f32_dpp v112, v112, v112 row_ror:4 row_mask:0xf bank_mask:0xf
	v_add_f32_dpp v113, v113, v113 row_ror:4 row_mask:0xf bank_mask:0xf
	v_add_f32_dpp v114, v114, v114 row_ror:4 row_mask:0xf bank_mask:0xf
	v_add_f32_dpp v115, v115, v115 row_ror:4 row_mask:0xf bank_mask:0xf
	v_add_f32_dpp v112, v112, v112 row_ror:2 row_mask:0xf bank_mask:0xf
	v_add_f32_dpp v113, v113, v113 row_ror:2 row_mask:0xf bank_mask:0xf
	v_add_f32_dpp v114, v114, v114 row_ror:2 row_mask:0xf bank_mask:0xf
	v_add_f32_dpp v115, v115, v115 row_ror:2 row_mask:0xf bank_mask:0xf
	v_add_f32_dpp v112, v112, v112 row_ror:1 row_mask:0xf bank_mask:0xf
	v_add_f32_dpp v113, v113, v113 row_ror:1 row_mask:0xf bank_mask:0xf
	v_add_f32_dpp v114, v114, v114 row_ror:1 row_mask:0xf bank_mask:0xf
	v_add_f32_dpp v115, v115, v115 row_ror:1 row_mask:0xf bank_mask:0xf
	s_mov_b64 s[26:27], exec
	s_and_b64 exec, exec, s[22:23]
	ds_write_b128 v148, v[112:115] offset:39168
	s_mov_b64 exec, s[26:27]
	s_waitcnt lgkmcnt(1)
	v_pk_add_f32 v[220:221], v[204:205], v[208:209]
	v_pk_add_f32 v[222:223], v[206:207], v[210:211]
	v_pk_add_f32 v[220:221], v[220:221], v[212:213]
	v_pk_add_f32 v[222:223], v[222:223], v[214:215]
	v_pk_add_f32 v[220:221], v[220:221], v[216:217]
	v_pk_add_f32 v[222:223], v[222:223], v[218:219]
	v_fma_f32 v220, v220, s30, v177
	v_fma_f32 v221, v221, s30, v177
	v_fma_f32 v222, v222, s30, v177
	v_fma_f32 v223, v223, s30, v177
	v_rsq_f32_e32 v220, v220
	v_rsq_f32_e32 v221, v221
	v_rsq_f32_e32 v222, v222
	v_rsq_f32_e32 v223, v223
	s_nop 0
	v_mul_f32_e32 v204, v186, v220
	v_mul_f32_e32 v205, v187, v221
	v_mul_f32_e32 v206, v188, v222
	v_mul_f32_e32 v207, v189, v223
	v_mul_f32_e32 v208, v190, v220
	v_mul_f32_e32 v209, v191, v221
	v_mul_f32_e32 v210, v192, v222
	v_mul_f32_e32 v211, v193, v223
	v_mul_f32_e32 v204, v175, v204
	v_mul_f32_e32 v205, v175, v205
	v_mul_f32_e32 v206, v175, v206
	v_mul_f32_e32 v207, v175, v207
	v_mul_f32_e32 v208, v176, v208
	v_mul_f32_e32 v209, v176, v209
	v_mul_f32_e32 v210, v176, v210
	v_mul_f32_e32 v211, v176, v211
	ds_write_b32 v149, v204 offset:39424
	ds_write_b32 v149, v205 offset:39952
	ds_write_b32 v149, v206 offset:40480
	ds_write_b32 v149, v207 offset:41008
	ds_write_b32 v149, v208 offset:39488
	ds_write_b32 v149, v209 offset:40016
	ds_write_b32 v149, v210 offset:40544
	ds_write_b32 v149, v211 offset:41072
	s_cmp_lg_u32 s29, 0
	s_cbranch_scc1 .Lrec_hg_p1w_d
	s_waitcnt vmcnt(9)
	s_branch .Lrec_hg_p1w_c

; template <int DK, bool HG, int MODE>
; __device__ void recur_unit(const Params& p, char* smem, int b, int h, char* img, int nstart, int nstep, int nend) {
;     ...
;   auto step = [&](int n, u32x4 (&im)[NIM], u16 (&psg)[8]) {
;     float sgate[8];
;     if (MODE == 2) {
; #pragma unroll
;       for (int i = 0; i < NIM; i++) if (tid * 16 + 4096 * i < IMG) *(u32x4*)(smem + tid * 16 + 4096 * i) = im[i];
;       {
;         u32x4 g;
;         g[0] = (unsigned)psg[0] | ((unsigned)psg[1] << 16); g[1] = (unsigned)psg[2] | ((unsigned)psg[3] << 16);
;         g[2] = (unsigned)psg[4] | ((unsigned)psg[5] << 16); g[3] = (unsigned)psg[6] | ((unsigned)psg[7] << 16);
;         *(u32x4*)&GT[(tid >> 4) * 136 + (tid & 15) * 8] = g;
;       }
;       __builtin_amdgcn_sched_barrier(0);
;       if (n + PFD * nstep < nend) prefetch(n + PFD * nstep, im, psg);
;       __builtin_amdgcn_sched_barrier(0);
.Lrec_hg_p1w_c:
	ds_write_b128 v151, v[0:3] offset:0
	ds_write_b128 v151, v[4:7] offset:4096
	ds_write_b128 v151, v[8:11] offset:8192
	ds_write_b128 v151, v[12:15] offset:12288
	s_mov_b64 s[26:27], exec
	s_and_b64 exec, exec, s[24:25]
	ds_write_b128 v151, v[16:19] offset:16384
	s_mov_b64 exec, s[26:27]
	s_cmp_gt_u32 s36, 124
	s_cbranch_scc1 .Lrec_hg_p1_nol
	global_load_dwordx4 v[0:3], v152, s[8:9]
	global_load_dwordx4 v[4:7], v153, s[8:9]
	global_load_dwordx4 v[8:11], v154, s[8:9]
	global_load_dwordx4 v[12:15], v155, s[8:9]
	global_load_dwordx4 v[16:19], v172, s[8:9]
	s_add_u32 s8, s8, 0x4c00
	s_addc_u32 s9, s9, 0

; __device__ __forceinline__ unsigned xb_ld(unsigned* p)              { return __hip_atomic_load(p, __ATOMIC_RELAXED, __HIP_MEMORY_SCOPE_AGENT); }
; __device__ __forceinline__ unsigned xb_add(unsigned* p, unsigned v) { return __hip_atomic_fetch_add(p, v, __ATOMIC_RELAXED, __HIP_MEMORY_SCOPE_AGENT); }
; #define XB_SPIN(cond, bar) do { unsigned _sp = 0; while (cond) { __builtin_amdgcn_s_sleep(1); \
;     if ((++_sp & 255u) == 0u) { if (xb_ld(&(bar)[XB_TMO])) break; if (_sp > XB_SPIN_CAP) { atomicAdd(&(bar)[XB_TMO], 1u); break; } } } } while (0)
; __device__ __forceinline__ void xcd_barrier(const XcdBarrier& b) {
;     ...
;       else XB_SPIN(xb_ld(&bar[XB_TOPGEN]) == tg, bar);
;       __builtin_amdgcn_fence(__ATOMIC_ACQUIRE, "agent");
;       xb_add(&bar[XB_XGEN(b.x)], 1u);
;       asm volatile("s_waitcnt vmcnt(0)" ::: "memory");
;     } else {
;       XB_SPIN(xb_ld(&bar[XB_XGEN(b.x)]) == gen, bar);
.LBB0_708:
	s_cmp_lt_u32 s44, 0x40001
	s_mov_b64 s[40:41], 0
	s_cselect_b64 s[2:3], -1, 0
	s_and_b64 vcc, exec, s[2:3]
	s_cbranch_vccz .LBB0_701
	s_branch .LBB0_707
.LBB0_718:
	s_andn2_b64 vcc, exec, s[40:41]
	s_cbranch_vccz .LBB0_722
	s_mov_b64 s[40:41], exec
	v_mbcnt_lo_u32_b32 v159, s40, 0
	v_mbcnt_hi_u32_b32 v159, s41, v159
	v_cmp_eq_u32_e32 vcc, 0, v159
	s_and_saveexec_b64 s[2:3], vcc
	s_cbranch_execz .LBB0_721
	s_bcnt1_i32_b64 s6, s[40:41]
	v_mov_b32_e32 v159, s6
	global_atomic_add v143, v159, s[54:55]

; #define LAS __attribute__((address_space(3)))
; __device__ __forceinline__ unsigned xb_xcc_id() { return (unsigned)__builtin_amdgcn_s_getreg((3 << 11) | 20) & 0xFu; }
; template <int DK, bool HG, int MODE>
; __device__ void recur_unit(const Params& p, char* smem, int b, int h, char* img, int nstart, int nstep, int nend) {
;     ...
;       if (n == 62) mid_barrier(p, smem);
;       step(n, imA, psg); step(n + 1, imB, psgB);
; __device__ __forceinline__ void xcd_barrier(const XcdBarrier& b) {
;     ...
;   __syncthreads();
; }
; __device__ void mid_barrier(const Params& p, char* smem) {
;   XcdBarrier b; b.bar = p.bar; b.x = xb_xcc_id(); b.st = (volatile LAS unsigned*)(smem + 2 * GEMM_SMEM + 768);
;   xcd_barrier(b);
; }
.LBB0_759:
	s_or_b64 exec, exec, s[38:39]
	s_waitcnt lgkmcnt(0)
	s_barrier
	s_cmp_eq_u32 s4, 0
	s_cbranch_scc1 .Lrec_hg_midret
	s_branch .Lrec_gla_midret

; __global__ void __launch_bounds__(256, 2) fwd_megakernel(Params p) {
;   extern __shared__ __attribute__((aligned(16))) char smem[];
	.amdhsa_kernel _Z14fwd_megakernel6Params
		.amdhsa_group_segment_fixed_size 0
		.amdhsa_private_segment_fixed_size 0
		.amdhsa_kernarg_size 584
		.amdhsa_user_sgpr_count 2
		.amdhsa_user_sgpr_dispatch_ptr 0
		.amdhsa_user_sgpr_queue_ptr 0
		.amdhsa_user_sgpr_kernarg_segment_ptr 1
		.amdhsa_user_sgpr_dispatch_id 0
		.amdhsa_user_sgpr_kernarg_preload_length 0
		.amdhsa_user_sgpr_kernarg_preload_offset 0
		.amdhsa_user_sgpr_private_segment_size 0
		.amdhsa_uses_dynamic_stack 0
		.amdhsa_enable_private_segment 0
		.amdhsa_system_sgpr_workgroup_id_x 1
		.amdhsa_system_sgpr_workgroup_id_y 0
		.amdhsa_system_sgpr_workgroup_id_z 0
		.amdhsa_system_sgpr_workgroup_info 0
		.amdhsa_system_vgpr_workitem_id 2
		.amdhsa_next_free_vgpr 256
		.amdhsa_next_free_sgpr 98
		.amdhsa_accum_offset 244
		.amdhsa_reserve_vcc 1
		.amdhsa_float_round_mode_32 0
		.amdhsa_float_round_mode_16_64 0
		.amdhsa_float_denorm_mode_32 3
		.amdhsa_float_denorm_mode_16_64 3
		.amdhsa_dx10_clamp 1
		.amdhsa_ieee_mode 1
		.amdhsa_fp16_overflow 0
		.amdhsa_tg_split 0
		.amdhsa_exception_fp_ieee_invalid_op 0
		.amdhsa_exception_fp_denorm_src 0
		.amdhsa_exception_fp_ieee_div_zero 0
		.amdhsa_exception_fp_ieee_overflow 0
		.amdhsa_exception_fp_ieee_underflow 0
		.amdhsa_exception_fp_ieee_inexact 0
		.amdhsa_exception_int_div_zero 0
	.end_amdhsa_kernel

amdhsa.kernels:
  - .agpr_count:     12
    .args:
      - .offset:         0
        .size:           328
        .value_kind:     by_value
      - .offset:         328
        .size:           4
        .value_kind:     hidden_block_count_x
      - .offset:         332
        .size:           4
        .value_kind:     hidden_block_count_y
      - .offset:         336
        .size:           4
        .value_kind:     hidden_block_count_z
      - .offset:         340
        .size:           2
        .value_kind:     hidden_group_size_x
      - .offset:         342
        .size:           2
        .value_kind:     hidden_group_size_y
      - .offset:         344
        .size:           2
        .value_kind:     hidden_group_size_z
      - .offset:         346
        .size:           2
        .value_kind:     hidden_remainder_x
      - .offset:         348
        .size:           2
        .value_kind:     hidden_remainder_y
      - .offset:         350
        .size:           2
        .value_kind:     hidden_remainder_z
      - .offset:         368
        .size:           8
        .value_kind:     hidden_global_offset_x
      - .offset:         376
        .size:           8
        .value_kind:     hidden_global_offset_y
      - .offset:         384
        .size:           8
        .value_kind:     hidden_global_offset_z
      - .offset:         392
        .size:           2
        .value_kind:     hidden_grid_dims
      - .offset:         416
        .size:           8
        .value_kind:     hidden_multigrid_sync_arg
      - .offset:         448
        .size:           4
        .value_kind:     hidden_dynamic_lds_size
    .group_segment_fixed_size: 0
    .kernarg_segment_align: 8
    .kernarg_segment_size: 584
    .language:       OpenCL C
    .language_version:
      - 2
      - 0
    .max_flat_workgroup_size: 256
    .name:           _Z14fwd_megakernel6Params
    .private_segment_fixed_size: 0
    .sgpr_count:     104
    .sgpr_spill_count: 57
    .symbol:         _Z14fwd_megakernel6Params.kd
    .uniform_work_group_size: 1
    .uses_dynamic_stack: false
    .vgpr_count:     244
    .vgpr_spill_count: 0
    .wavefront_size: 64
